# route score loops: all eight key-fragment LDS reads issued up front with counted lgkmcnt
# baseline (speedup 1.0000x reference)
; __device__ __forceinline__ unsigned ordf(float f) { unsigned u = __float_as_uint(f); return u ^ ((unsigned)((int)u >> 31) | 0x80000000u); }
; __device__ __forceinline__ void route_half(const unsigned char* kp, const bf16* qptr, int r, int hf, unsigned (&L)[16]) {
;     ...
;     for (int blk = 0; blk < 4; ++blk) {
;         f32x16 sc;
; #pragma unroll
;         for (int i = 0; i < 16; ++i) sc[i] = 0.f;
; #pragma unroll
;         for (int ks = 0; ks < 8; ++ks) { const bf16x8 a = *(const bf16x8*)(kp + (blk * 32 + r) * RT_KP + (16 * ks + 8 * hf) * 2);
;             sc = __builtin_amdgcn_mfma_f32_32x32x16_bf16(a, qf[ks], sc, 0, 0, 0); }
;         unsigned kv[16];
; #pragma unroll
;         for (int i = 0; i < 16; ++i) { const unsigned n = (unsigned)(blk * 32 + (i & 3) + 8 * (i >> 2) + 4 * hf); kv[i] = (ordf(sc[i]) & ~0x7Fu) | n; }
;         sort16_desc(kv); merge16_desc(L, kv);
.LBB0_132:
	ds_read_b128 v[2:5], v52
	ds_read_b128 v[84:87], v52 offset:32
	ds_read_b128 v[200:203], v52 offset:64
	ds_read_b128 v[204:207], v52 offset:96
	ds_read_b128 v[208:211], v52 offset:128
	ds_read_b128 v[212:215], v52 offset:160
	ds_read_b128 v[216:219], v52 offset:192
	ds_read_b128 v[220:223], v52 offset:224
	v_add_u32_e32 v52, 0x2200, v52
	s_waitcnt vmcnt(0) lgkmcnt(7)
	v_mfma_f32_32x32x16_bf16 v[2:17], v[2:5], v[18:21], 0
	s_waitcnt vmcnt(6) lgkmcnt(6)
	v_mfma_f32_32x32x16_bf16 v[2:17], v[84:87], v[22:25], v[2:17]
	s_waitcnt vmcnt(5) lgkmcnt(5)
	v_mfma_f32_32x32x16_bf16 v[2:17], v[200:203], v[26:29], v[2:17]
	s_waitcnt vmcnt(4) lgkmcnt(4)
	v_mfma_f32_32x32x16_bf16 v[2:17], v[204:207], v[30:33], v[2:17]
	s_waitcnt vmcnt(3) lgkmcnt(3)
	v_mfma_f32_32x32x16_bf16 v[2:17], v[208:211], v[34:37], v[2:17]
	s_waitcnt vmcnt(2) lgkmcnt(2)
	v_mfma_f32_32x32x16_bf16 v[2:17], v[212:215], v[38:41], v[2:17]
	s_waitcnt vmcnt(1) lgkmcnt(1)
	v_mfma_f32_32x32x16_bf16 v[2:17], v[216:219], v[42:45], v[2:17]
	s_waitcnt vmcnt(0) lgkmcnt(0)
	v_mfma_f32_32x32x16_bf16 v[2:17], v[220:223], v[46:49], v[2:17]
	s_nop 11
	v_ashrrev_i32_e32 v83, 31, v3
	v_or_b32_e32 v83, 0x80000000, v83
	v_bitop3_b32 v3, v83, s81, v3 bitop3:0x48
	v_ashrrev_i32_e32 v83, 31, v4
	v_or_b32_e32 v83, 0x80000000, v83
	v_bitop3_b32 v4, v83, s81, v4 bitop3:0x48
	v_ashrrev_i32_e32 v83, 31, v5
	v_or_b32_e32 v83, 0x80000000, v83
	v_bitop3_b32 v5, v83, s81, v5 bitop3:0x48
	v_ashrrev_i32_e32 v83, 31, v6
	v_or_b32_e32 v83, 0x80000000, v83
	v_bitop3_b32 v6, v83, s81, v6 bitop3:0x48
	v_ashrrev_i32_e32 v83, 31, v7
	v_or_b32_e32 v83, 0x80000000, v83
	v_bitop3_b32 v7, v83, s81, v7 bitop3:0x48
	v_ashrrev_i32_e32 v83, 31, v8
	v_or_b32_e32 v83, 0x80000000, v83
	v_bitop3_b32 v8, v83, s81, v8 bitop3:0x48
	v_ashrrev_i32_e32 v83, 31, v9
	v_or_b32_e32 v83, 0x80000000, v83
	v_bitop3_b32 v9, v83, s81, v9 bitop3:0x48
	v_ashrrev_i32_e32 v83, 31, v10
	v_or_b32_e32 v83, 0x80000000, v83
	v_bitop3_b32 v10, v83, s81, v10 bitop3:0x48
	v_ashrrev_i32_e32 v83, 31, v11
	v_or_b32_e32 v83, 0x80000000, v83
	v_bitop3_b32 v11, v83, s81, v11 bitop3:0x48
	v_ashrrev_i32_e32 v83, 31, v12
	v_or_b32_e32 v83, 0x80000000, v83
	v_bitop3_b32 v12, v83, s81, v12 bitop3:0x48
	v_ashrrev_i32_e32 v83, 31, v13
	v_or_b32_e32 v83, 0x80000000, v83
	v_bitop3_b32 v13, v83, s81, v13 bitop3:0x48
	v_ashrrev_i32_e32 v83, 31, v14
	v_or_b32_e32 v83, 0x80000000, v83
	v_bitop3_b32 v14, v83, s81, v14 bitop3:0x48
	v_ashrrev_i32_e32 v83, 31, v15
	v_or_b32_e32 v83, 0x80000000, v83
	v_bitop3_b32 v15, v83, s81, v15 bitop3:0x48
	v_ashrrev_i32_e32 v83, 31, v16
	v_or_b32_e32 v83, 0x80000000, v83
	v_ashrrev_i32_e32 v53, 31, v2
	v_bitop3_b32 v16, v83, s81, v16 bitop3:0x48
	v_ashrrev_i32_e32 v83, 31, v17
	v_or_b32_e32 v53, 0x80000000, v53
	v_or_b32_e32 v83, 0x80000000, v83
	v_bitop3_b32 v2, v53, s81, v2 bitop3:0x48
	v_add_u32_e32 v53, s4, v63
	v_bitop3_b32 v17, v83, s81, v17 bitop3:0x48
	v_add_u32_e32 v2, v53, v2
	v_add3_u32 v3, v53, v3, 1
	v_add3_u32 v4, v53, v4, 2
	v_add3_u32 v5, v53, v5, 3
	v_add3_u32 v6, v53, v6, 8
	v_add3_u32 v7, v53, v7, 9
	v_add3_u32 v8, v53, v8, 10
	v_add3_u32 v9, v53, v9, 11
	v_add3_u32 v10, v53, v10, 16
	v_add3_u32 v11, v53, v11, 17
	v_add3_u32 v12, v53, v12, 18
	v_add3_u32 v13, v53, v13, 19
	v_add3_u32 v14, v53, v14, 24
	v_add3_u32 v15, v53, v15, 25
	v_add3_u32 v16, v53, v16, 26
	v_add3_u32 v17, v53, v17, 27
	v_max_u32_e32 v53, v2, v3
	v_min_u32_e32 v2, v2, v3
	v_max_u32_e32 v3, v5, v4
	v_min_u32_e32 v4, v5, v4
	v_max_u32_e32 v5, v6, v7
	v_min_u32_e32 v6, v6, v7
	v_max_u32_e32 v7, v9, v8
	v_min_u32_e32 v8, v9, v8
	v_max_u32_e32 v9, v10, v11
	v_min_u32_e32 v10, v10, v11
	v_max_u32_e32 v11, v13, v12
	v_min_u32_e32 v12, v13, v12
	v_max_u32_e32 v13, v14, v15
	v_min_u32_e32 v14, v14, v15
	v_max_u32_e32 v15, v17, v16
	v_min_u32_e32 v16, v17, v16
	v_max_u32_e32 v17, v53, v4
	v_min_u32_e32 v4, v53, v4
	v_max_u32_e32 v53, v2, v3
	v_min_u32_e32 v2, v2, v3
	v_max_u32_e32 v3, v8, v5
	v_min_u32_e32 v5, v8, v5
	v_max_u32_e32 v8, v7, v6
	v_min_u32_e32 v6, v7, v6
	v_max_u32_e32 v7, v9, v12
	v_min_u32_e32 v9, v9, v12
	v_max_u32_e32 v12, v10, v11
	v_min_u32_e32 v10, v10, v11
	v_max_u32_e32 v11, v16, v13
	v_min_u32_e32 v13, v16, v13
	v_max_u32_e32 v16, v15, v14
	v_min_u32_e32 v14, v15, v14
	v_max_u32_e32 v15, v17, v53
	v_min_u32_e32 v17, v17, v53
	v_max_u32_e32 v53, v4, v2
	v_min_u32_e32 v2, v4, v2
	v_max_u32_e32 v4, v6, v5
	v_min_u32_e32 v5, v6, v5
	v_max_u32_e32 v6, v8, v3
	v_min_u32_e32 v3, v8, v3
	v_max_u32_e32 v8, v7, v12
	v_min_u32_e32 v7, v7, v12
	v_max_u32_e32 v12, v9, v10
	v_min_u32_e32 v9, v9, v10
	v_max_u32_e32 v10, v14, v13
	v_min_u32_e32 v13, v14, v13
	v_max_u32_e32 v14, v16, v11
	v_min_u32_e32 v11, v16, v11
	v_max_u32_e32 v16, v15, v5
	v_min_u32_e32 v5, v15, v5
	v_max_u32_e32 v15, v17, v4
	v_min_u32_e32 v4, v17, v4
	v_max_u32_e32 v17, v53, v3
	v_min_u32_e32 v3, v53, v3
	v_max_u32_e32 v53, v2, v6
	v_min_u32_e32 v2, v2, v6
	v_max_u32_e32 v6, v13, v8
	v_min_u32_e32 v8, v13, v8
	v_max_u32_e32 v13, v10, v7
	v_min_u32_e32 v7, v10, v7
	v_max_u32_e32 v10, v11, v12
	v_min_u32_e32 v11, v11, v12
	v_max_u32_e32 v12, v14, v9
	v_min_u32_e32 v9, v14, v9
	v_max_u32_e32 v14, v16, v17
	v_min_u32_e32 v16, v16, v17
	v_max_u32_e32 v17, v15, v53
	v_min_u32_e32 v15, v15, v53
	v_max_u32_e32 v53, v5, v3
	v_min_u32_e32 v3, v5, v3
	v_max_u32_e32 v5, v4, v2
	v_min_u32_e32 v2, v4, v2
	v_max_u32_e32 v4, v11, v8
	v_min_u32_e32 v8, v11, v8
	v_max_u32_e32 v11, v9, v7
	v_min_u32_e32 v7, v9, v7
	v_max_u32_e32 v9, v10, v6
	v_min_u32_e32 v6, v10, v6
	v_max_u32_e32 v10, v12, v13
	v_min_u32_e32 v12, v12, v13
	v_max_u32_e32 v13, v14, v17
	v_min_u32_e32 v14, v14, v17
; __device__ __forceinline__ void route_half(const unsigned char* kp, const bf16* qptr, int r, int hf, unsigned (&L)[16]) {
;     ...
;         sort16_desc(kv); merge16_desc(L, kv);
;     }
;     unsigned pk[16];
; #pragma unroll
;     for (int j = 0; j < 16; ++j) pk[j] = (unsigned)__shfl_xor((int)L[j], 32);
	v_max_u32_e32 v17, v16, v15
	v_min_u32_e32 v15, v16, v15
	v_max_u32_e32 v16, v53, v5
	v_min_u32_e32 v5, v53, v5
	v_max_u32_e32 v53, v3, v2
	v_min_u32_e32 v2, v3, v2
	v_max_u32_e32 v3, v7, v8
	v_min_u32_e32 v7, v7, v8
	v_max_u32_e32 v8, v11, v4
	v_min_u32_e32 v4, v11, v4
	v_max_u32_e32 v11, v12, v6
	v_min_u32_e32 v6, v12, v6
	v_max_u32_e32 v12, v10, v9
	v_min_u32_e32 v9, v10, v9
	v_max_u32_e32 v10, v13, v7
	v_min_u32_e32 v7, v13, v7
	v_max_u32_e32 v13, v14, v3
	v_min_u32_e32 v3, v14, v3
	v_max_u32_e32 v14, v17, v4
	v_min_u32_e32 v4, v17, v4
	v_max_u32_e32 v17, v15, v8
	v_min_u32_e32 v8, v15, v8
	v_max_u32_e32 v15, v16, v6
	v_min_u32_e32 v6, v16, v6
	v_max_u32_e32 v16, v5, v11
	v_min_u32_e32 v5, v5, v11
	v_max_u32_e32 v11, v53, v9
	v_min_u32_e32 v9, v53, v9
	v_max_u32_e32 v53, v2, v12
	v_min_u32_e32 v2, v2, v12
	v_max_u32_e32 v12, v10, v15
	v_min_u32_e32 v10, v10, v15
	v_max_u32_e32 v15, v13, v16
	v_min_u32_e32 v13, v13, v16
	v_max_u32_e32 v16, v14, v11
	v_min_u32_e32 v11, v14, v11
	v_max_u32_e32 v14, v17, v53
	v_min_u32_e32 v17, v17, v53
	v_max_u32_e32 v53, v7, v6
	v_min_u32_e32 v6, v7, v6
	v_max_u32_e32 v7, v3, v5
	v_min_u32_e32 v3, v3, v5
	v_max_u32_e32 v5, v4, v9
	v_min_u32_e32 v4, v4, v9
	v_max_u32_e32 v9, v8, v2
	v_min_u32_e32 v2, v8, v2
	v_max_u32_e32 v8, v12, v16
	v_min_u32_e32 v12, v12, v16
	v_max_u32_e32 v16, v15, v14
	v_min_u32_e32 v14, v15, v14
	v_max_u32_e32 v15, v10, v11
	v_min_u32_e32 v10, v10, v11
	v_max_u32_e32 v11, v13, v17
	v_min_u32_e32 v13, v13, v17
	v_max_u32_e32 v17, v53, v5
	v_min_u32_e32 v5, v53, v5
	v_max_u32_e32 v53, v7, v9
	v_min_u32_e32 v7, v7, v9
	v_max_u32_e32 v9, v6, v4
	v_min_u32_e32 v4, v6, v4
	v_max_u32_e32 v6, v3, v2
	v_min_u32_e32 v2, v3, v2
	v_min_u32_e32 v3, v8, v16
	v_min_u32_e32 v83, v12, v14
	v_min_u32_e32 v84, v15, v11
	v_min_u32_e32 v85, v10, v13
	v_min_u32_e32 v86, v17, v53
	v_min_u32_e32 v87, v5, v7
	v_min_u32_e32 v88, v9, v6
	v_min_u32_e32 v89, v4, v2
	v_max_u32_e32 v67, v67, v89
	v_max3_u32 v2, v68, v4, v2
	v_max_u32_e32 v4, v69, v88
	v_max3_u32 v6, v70, v9, v6
	v_max_u32_e32 v9, v71, v87
	v_max3_u32 v5, v72, v5, v7
	v_max_u32_e32 v7, v73, v86
	v_max3_u32 v17, v74, v17, v53
	v_max_u32_e32 v53, v75, v85
	v_max3_u32 v10, v76, v10, v13
	v_max_u32_e32 v13, v77, v84
	v_max3_u32 v11, v78, v15, v11
	v_max_u32_e32 v15, v79, v83
	v_max3_u32 v12, v80, v12, v14
	v_max_u32_e32 v3, v81, v3
	v_max3_u32 v8, v82, v8, v16
	v_max_u32_e32 v14, v67, v53
	v_min_u32_e32 v16, v67, v53
	v_max_u32_e32 v53, v2, v10
	v_min_u32_e32 v2, v2, v10
	v_max_u32_e32 v10, v4, v13
	v_min_u32_e32 v4, v4, v13
	v_max_u32_e32 v13, v6, v11
	v_min_u32_e32 v6, v6, v11
	v_max_u32_e32 v11, v9, v15
	v_min_u32_e32 v9, v9, v15
	v_max_u32_e32 v15, v5, v12
	v_min_u32_e32 v5, v5, v12
	v_max_u32_e32 v12, v7, v3
	v_min_u32_e32 v3, v7, v3
	v_max_u32_e32 v7, v17, v8
	v_min_u32_e32 v8, v17, v8
	v_max_u32_e32 v17, v14, v11
	v_min_u32_e32 v11, v14, v11
	v_max_u32_e32 v14, v53, v15
	v_min_u32_e32 v15, v53, v15
	v_max_u32_e32 v53, v10, v12
	v_min_u32_e32 v10, v10, v12
	v_max_u32_e32 v12, v13, v7
	v_min_u32_e32 v7, v13, v7
	v_max_u32_e32 v13, v16, v9
	v_min_u32_e32 v9, v16, v9
	v_max_u32_e32 v16, v2, v5
	v_min_u32_e32 v2, v2, v5
	v_max_u32_e32 v5, v4, v3
	v_min_u32_e32 v3, v4, v3
	v_max_u32_e32 v4, v6, v8
	v_min_u32_e32 v6, v6, v8
	v_max_u32_e32 v8, v17, v53
	v_min_u32_e32 v17, v17, v53
	v_max_u32_e32 v53, v14, v12
	v_min_u32_e32 v12, v14, v12
	v_max_u32_e32 v14, v11, v10
	v_min_u32_e32 v10, v11, v10
	v_max_u32_e32 v11, v15, v7
	v_min_u32_e32 v7, v15, v7
	v_max_u32_e32 v15, v13, v5
	v_min_u32_e32 v5, v13, v5
	v_max_u32_e32 v13, v16, v4
	v_min_u32_e32 v4, v16, v4
	v_max_u32_e32 v16, v9, v3
	v_min_u32_e32 v3, v9, v3
	v_max_u32_e32 v9, v2, v6
	v_min_u32_e32 v2, v2, v6
	s_add_i32 s4, s4, 32
	v_max_u32_e32 v67, v8, v53
	v_min_u32_e32 v68, v8, v53
	v_max_u32_e32 v69, v17, v12
	v_min_u32_e32 v70, v17, v12
	v_max_u32_e32 v71, v14, v11
	v_min_u32_e32 v72, v14, v11
	v_max_u32_e32 v73, v10, v7
	v_min_u32_e32 v74, v10, v7
	v_max_u32_e32 v75, v15, v13
	v_min_u32_e32 v76, v15, v13
	v_max_u32_e32 v77, v5, v4
	v_min_u32_e32 v78, v5, v4
	v_max_u32_e32 v79, v16, v9
	v_min_u32_e32 v80, v16, v9
	v_max_u32_e32 v81, v3, v2
	v_min_u32_e32 v82, v3, v2
	s_cmpk_lg_i32 s4, 0x80
	s_cbranch_scc1 .LBB0_132
	global_load_dwordx4 v[18:21], v[50:51], off offset:256
	global_load_dwordx4 v[22:25], v[50:51], off offset:288
	global_load_dwordx4 v[26:29], v[50:51], off offset:320
	global_load_dwordx4 v[30:33], v[50:51], off offset:352
	global_load_dwordx4 v[34:37], v[50:51], off offset:384
	global_load_dwordx4 v[38:41], v[50:51], off offset:416
	global_load_dwordx4 v[42:45], v[50:51], off offset:448
	global_load_dwordx4 v[46:49], v[50:51], off offset:480
	ds_bpermute_b32 v94, v64, v67
	ds_bpermute_b32 v97, v64, v68
	ds_bpermute_b32 v100, v64, v69
	ds_bpermute_b32 v102, v64, v70
	ds_bpermute_b32 v103, v64, v71
	ds_bpermute_b32 v104, v64, v72
	ds_bpermute_b32 v105, v64, v73
	ds_bpermute_b32 v106, v64, v74
	ds_bpermute_b32 v107, v64, v75
	ds_bpermute_b32 v108, v64, v76
	ds_bpermute_b32 v109, v64, v77
	ds_bpermute_b32 v110, v64, v78
	ds_bpermute_b32 v111, v64, v79
	ds_bpermute_b32 v112, v64, v80
	ds_bpermute_b32 v113, v64, v81
	ds_bpermute_b32 v114, v64, v82
	s_mov_b32 s0, 0
	v_mov_b32_e32 v83, 0
	v_mov_b32_e32 v91, 0
	v_mov_b32_e32 v84, 0
	v_mov_b32_e32 v92, 0
	v_mov_b32_e32 v85, 0
	v_mov_b32_e32 v93, 0
	v_mov_b32_e32 v86, 0
	v_mov_b32_e32 v95, 0
	v_mov_b32_e32 v87, 0
	v_mov_b32_e32 v96, 0
	v_mov_b32_e32 v88, 0
	v_mov_b32_e32 v98, 0
	v_mov_b32_e32 v89, 0
	v_mov_b32_e32 v99, 0
	v_mov_b32_e32 v90, 0
	v_mov_b32_e32 v101, 0
	v_mov_b32_e32 v115, v66
; __device__ __forceinline__ unsigned ordf(float f) { unsigned u = __float_as_uint(f); return u ^ ((unsigned)((int)u >> 31) | 0x80000000u); }
; __device__ __forceinline__ void route_half(const unsigned char* kp, const bf16* qptr, int r, int hf, unsigned (&L)[16]) {
;     ...
;     for (int blk = 0; blk < 4; ++blk) {
;         f32x16 sc;
; #pragma unroll
;         for (int i = 0; i < 16; ++i) sc[i] = 0.f;
; #pragma unroll
;         for (int ks = 0; ks < 8; ++ks) { const bf16x8 a = *(const bf16x8*)(kp + (blk * 32 + r) * RT_KP + (16 * ks + 8 * hf) * 2);
;             sc = __builtin_amdgcn_mfma_f32_32x32x16_bf16(a, qf[ks], sc, 0, 0, 0); }
;         unsigned kv[16];
; #pragma unroll
;         for (int i = 0; i < 16; ++i) { const unsigned n = (unsigned)(blk * 32 + (i & 3) + 8 * (i >> 2) + 4 * hf); kv[i] = (ordf(sc[i]) & ~0x7Fu) | n; }
;         sort16_desc(kv); merge16_desc(L, kv);
.LBB0_134:
	ds_read_b128 v[2:5], v115
	ds_read_b128 v[50:53], v115 offset:32
	ds_read_b128 v[200:203], v115 offset:64
	ds_read_b128 v[204:207], v115 offset:96
	ds_read_b128 v[208:211], v115 offset:128
	ds_read_b128 v[212:215], v115 offset:160
	ds_read_b128 v[216:219], v115 offset:192
	ds_read_b128 v[220:223], v115 offset:224
	v_add_u32_e32 v116, s0, v63
	s_add_i32 s0, s0, 32
	s_cmpk_lg_i32 s0, 0x80
	v_add_u32_e32 v115, 0x2200, v115
	s_waitcnt vmcnt(7) lgkmcnt(7)
	v_mfma_f32_32x32x16_bf16 v[2:17], v[2:5], v[18:21], 0
	s_waitcnt vmcnt(6) lgkmcnt(6)
	v_mfma_f32_32x32x16_bf16 v[2:17], v[50:53], v[22:25], v[2:17]
	s_waitcnt vmcnt(5) lgkmcnt(5)
	v_mfma_f32_32x32x16_bf16 v[2:17], v[200:203], v[26:29], v[2:17]
	s_waitcnt vmcnt(4) lgkmcnt(4)
	v_mfma_f32_32x32x16_bf16 v[2:17], v[204:207], v[30:33], v[2:17]
	s_waitcnt vmcnt(3) lgkmcnt(3)
	v_mfma_f32_32x32x16_bf16 v[2:17], v[208:211], v[34:37], v[2:17]
	s_waitcnt vmcnt(2) lgkmcnt(2)
	v_mfma_f32_32x32x16_bf16 v[2:17], v[212:215], v[38:41], v[2:17]
	s_waitcnt vmcnt(1) lgkmcnt(1)
	v_mfma_f32_32x32x16_bf16 v[2:17], v[216:219], v[42:45], v[2:17]
	s_waitcnt vmcnt(0) lgkmcnt(0)
	v_mfma_f32_32x32x16_bf16 v[2:17], v[220:223], v[46:49], v[2:17]
	s_nop 11
	v_ashrrev_i32_e32 v50, 31, v2
	v_ashrrev_i32_e32 v51, 31, v3
	v_ashrrev_i32_e32 v52, 31, v4
	v_ashrrev_i32_e32 v53, 31, v5
	v_ashrrev_i32_e32 v117, 31, v6
	v_ashrrev_i32_e32 v118, 31, v7
	v_ashrrev_i32_e32 v119, 31, v8
	v_ashrrev_i32_e32 v120, 31, v9
	v_ashrrev_i32_e32 v121, 31, v10
	v_ashrrev_i32_e32 v122, 31, v11
	v_ashrrev_i32_e32 v123, 31, v12
	v_ashrrev_i32_e32 v124, 31, v13
	v_ashrrev_i32_e32 v125, 31, v14
	v_ashrrev_i32_e32 v126, 31, v15
	v_ashrrev_i32_e32 v127, 31, v16
	v_ashrrev_i32_e32 v128, 31, v17
	v_or_b32_e32 v50, 0x80000000, v50
	v_or_b32_e32 v51, 0x80000000, v51
	v_or_b32_e32 v52, 0x80000000, v52
	v_or_b32_e32 v53, 0x80000000, v53
	v_or_b32_e32 v117, 0x80000000, v117
	v_or_b32_e32 v118, 0x80000000, v118
	v_or_b32_e32 v119, 0x80000000, v119
	v_or_b32_e32 v120, 0x80000000, v120
	v_or_b32_e32 v121, 0x80000000, v121
	v_or_b32_e32 v122, 0x80000000, v122
	v_or_b32_e32 v123, 0x80000000, v123
	v_or_b32_e32 v124, 0x80000000, v124
	v_or_b32_e32 v125, 0x80000000, v125
	v_or_b32_e32 v126, 0x80000000, v126
	v_or_b32_e32 v127, 0x80000000, v127
	v_or_b32_e32 v128, 0x80000000, v128
	v_bitop3_b32 v2, v50, s81, v2 bitop3:0x48
	v_bitop3_b32 v3, v51, s81, v3 bitop3:0x48
	v_bitop3_b32 v4, v52, s81, v4 bitop3:0x48
	v_bitop3_b32 v5, v53, s81, v5 bitop3:0x48
	v_bitop3_b32 v6, v117, s81, v6 bitop3:0x48
	v_bitop3_b32 v7, v118, s81, v7 bitop3:0x48
	v_bitop3_b32 v8, v119, s81, v8 bitop3:0x48
	v_bitop3_b32 v9, v120, s81, v9 bitop3:0x48
	v_bitop3_b32 v10, v121, s81, v10 bitop3:0x48
	v_bitop3_b32 v11, v122, s81, v11 bitop3:0x48
	v_bitop3_b32 v12, v123, s81, v12 bitop3:0x48
	v_bitop3_b32 v13, v124, s81, v13 bitop3:0x48
	v_bitop3_b32 v14, v125, s81, v14 bitop3:0x48
	v_bitop3_b32 v15, v126, s81, v15 bitop3:0x48
	v_bitop3_b32 v16, v127, s81, v16 bitop3:0x48
	v_bitop3_b32 v17, v128, s81, v17 bitop3:0x48
	v_add_u32_e32 v2, v116, v2
	v_add3_u32 v3, v116, v3, 1
	v_add3_u32 v4, v116, v4, 2
	v_add3_u32 v5, v116, v5, 3
	v_add3_u32 v6, v116, v6, 8
	v_add3_u32 v7, v116, v7, 9
	v_add3_u32 v8, v116, v8, 10
	v_add3_u32 v9, v116, v9, 11
	v_add3_u32 v10, v116, v10, 16
	v_add3_u32 v11, v116, v11, 17
	v_add3_u32 v12, v116, v12, 18
	v_add3_u32 v13, v116, v13, 19
	v_add3_u32 v14, v116, v14, 24
	v_add3_u32 v15, v116, v15, 25
	v_add3_u32 v16, v116, v16, 26
	v_add3_u32 v17, v116, v17, 27
	v_max_u32_e32 v50, v2, v3
	v_min_u32_e32 v2, v2, v3
	v_max_u32_e32 v3, v5, v4
	v_min_u32_e32 v4, v5, v4
	v_max_u32_e32 v5, v6, v7
	v_min_u32_e32 v6, v6, v7
	v_max_u32_e32 v7, v9, v8
	v_min_u32_e32 v8, v9, v8
	v_max_u32_e32 v9, v10, v11
	v_min_u32_e32 v10, v10, v11
	v_max_u32_e32 v11, v13, v12
	v_min_u32_e32 v12, v13, v12
	v_max_u32_e32 v13, v14, v15
	v_min_u32_e32 v14, v14, v15
	v_max_u32_e32 v15, v17, v16
	v_min_u32_e32 v16, v17, v16
	v_max_u32_e32 v17, v50, v4
	v_min_u32_e32 v4, v50, v4
	v_max_u32_e32 v50, v2, v3
	v_min_u32_e32 v2, v2, v3
	v_max_u32_e32 v3, v8, v5
	v_min_u32_e32 v5, v8, v5
	v_max_u32_e32 v8, v7, v6
	v_min_u32_e32 v6, v7, v6
	v_max_u32_e32 v7, v9, v12
	v_min_u32_e32 v9, v9, v12
	v_max_u32_e32 v12, v10, v11
	v_min_u32_e32 v10, v10, v11
	v_max_u32_e32 v11, v16, v13
	v_min_u32_e32 v13, v16, v13
	v_max_u32_e32 v16, v15, v14
	v_min_u32_e32 v14, v15, v14
	v_max_u32_e32 v15, v17, v50
	v_min_u32_e32 v17, v17, v50
	v_max_u32_e32 v50, v4, v2
	v_min_u32_e32 v2, v4, v2
	v_max_u32_e32 v4, v6, v5
	v_min_u32_e32 v5, v6, v5
	v_max_u32_e32 v6, v8, v3
	v_min_u32_e32 v3, v8, v3
	v_max_u32_e32 v8, v7, v12
	v_min_u32_e32 v7, v7, v12
	v_max_u32_e32 v12, v9, v10
	v_min_u32_e32 v9, v9, v10
	v_max_u32_e32 v10, v14, v13
	v_min_u32_e32 v13, v14, v13
	v_max_u32_e32 v14, v16, v11
	v_min_u32_e32 v11, v16, v11
	v_max_u32_e32 v16, v15, v5
	v_min_u32_e32 v5, v15, v5
	v_max_u32_e32 v15, v17, v4
	v_min_u32_e32 v4, v17, v4
	v_max_u32_e32 v17, v50, v3
	v_min_u32_e32 v3, v50, v3
	v_max_u32_e32 v50, v2, v6
	v_min_u32_e32 v2, v2, v6
	v_max_u32_e32 v6, v13, v8
	v_min_u32_e32 v8, v13, v8
	v_max_u32_e32 v13, v10, v7
	v_min_u32_e32 v7, v10, v7
	v_max_u32_e32 v10, v11, v12
	v_min_u32_e32 v11, v11, v12
	v_max_u32_e32 v12, v14, v9
	v_min_u32_e32 v9, v14, v9
	v_max_u32_e32 v14, v16, v17
	v_min_u32_e32 v16, v16, v17
	v_max_u32_e32 v17, v15, v50
	v_min_u32_e32 v15, v15, v50
	v_max_u32_e32 v50, v5, v3
	v_min_u32_e32 v3, v5, v3
	v_max_u32_e32 v5, v4, v2
	v_min_u32_e32 v2, v4, v2
	v_max_u32_e32 v4, v11, v8
	v_min_u32_e32 v8, v11, v8
	v_max_u32_e32 v11, v9, v7
	v_min_u32_e32 v7, v9, v7
	v_max_u32_e32 v9, v10, v6
	v_min_u32_e32 v6, v10, v6
; __device__ __forceinline__ unsigned ordf(float f) { unsigned u = __float_as_uint(f); return u ^ ((unsigned)((int)u >> 31) | 0x80000000u); }
; __device__ __forceinline__ void route_half(const unsigned char* kp, const bf16* qptr, int r, int hf, unsigned (&L)[16]) {
;     ...
;         for (int i = 0; i < 16; ++i) { const unsigned n = (unsigned)(blk * 32 + (i & 3) + 8 * (i >> 2) + 4 * hf); kv[i] = (ordf(sc[i]) & ~0x7Fu) | n; }
;         sort16_desc(kv); merge16_desc(L, kv);
	v_max_u32_e32 v10, v12, v13
	v_min_u32_e32 v12, v12, v13
	v_max_u32_e32 v13, v14, v17
	v_min_u32_e32 v14, v14, v17
	v_max_u32_e32 v17, v16, v15
	v_min_u32_e32 v15, v16, v15
	v_max_u32_e32 v16, v50, v5
	v_min_u32_e32 v5, v50, v5
	v_max_u32_e32 v50, v3, v2
	v_min_u32_e32 v2, v3, v2
	v_max_u32_e32 v3, v7, v8
	v_min_u32_e32 v7, v7, v8
	v_max_u32_e32 v8, v11, v4
	v_min_u32_e32 v4, v11, v4
	v_max_u32_e32 v11, v12, v6
	v_min_u32_e32 v6, v12, v6
	v_max_u32_e32 v12, v10, v9
	v_min_u32_e32 v9, v10, v9
	v_max_u32_e32 v10, v13, v7
	v_min_u32_e32 v7, v13, v7
	v_max_u32_e32 v13, v14, v3
	v_min_u32_e32 v3, v14, v3
	v_max_u32_e32 v14, v17, v4
	v_min_u32_e32 v4, v17, v4
	v_max_u32_e32 v17, v15, v8
	v_min_u32_e32 v8, v15, v8
	v_max_u32_e32 v15, v16, v6
	v_min_u32_e32 v6, v16, v6
	v_max_u32_e32 v16, v5, v11
	v_min_u32_e32 v5, v5, v11
	v_max_u32_e32 v11, v50, v9
	v_min_u32_e32 v9, v50, v9
	v_max_u32_e32 v50, v2, v12
	v_min_u32_e32 v2, v2, v12
	v_max_u32_e32 v12, v10, v15
	v_min_u32_e32 v10, v10, v15
	v_max_u32_e32 v15, v13, v16
	v_min_u32_e32 v13, v13, v16
	v_max_u32_e32 v16, v14, v11
	v_min_u32_e32 v11, v14, v11
	v_max_u32_e32 v14, v17, v50
	v_min_u32_e32 v17, v17, v50
	v_max_u32_e32 v50, v7, v6
	v_min_u32_e32 v6, v7, v6
	v_max_u32_e32 v7, v3, v5
	v_min_u32_e32 v3, v3, v5
	v_max_u32_e32 v5, v4, v9
	v_min_u32_e32 v4, v4, v9
	v_max_u32_e32 v9, v8, v2
	v_min_u32_e32 v2, v8, v2
	v_max_u32_e32 v8, v12, v16
	v_min_u32_e32 v12, v12, v16
	v_max_u32_e32 v16, v15, v14
	v_min_u32_e32 v14, v15, v14
	v_max_u32_e32 v15, v10, v11
	v_min_u32_e32 v10, v10, v11
	v_max_u32_e32 v11, v13, v17
	v_min_u32_e32 v13, v13, v17
	v_max_u32_e32 v17, v50, v5
	v_min_u32_e32 v5, v50, v5
	v_max_u32_e32 v50, v7, v9
	v_min_u32_e32 v7, v7, v9
	v_max_u32_e32 v9, v6, v4
	v_min_u32_e32 v4, v6, v4
	v_max_u32_e32 v6, v3, v2
	v_min_u32_e32 v2, v3, v2
	v_min_u32_e32 v3, v8, v16
	v_min_u32_e32 v51, v12, v14
	v_min_u32_e32 v52, v15, v11
	v_min_u32_e32 v53, v10, v13
	v_min_u32_e32 v116, v17, v50
	v_min_u32_e32 v117, v5, v7
	v_min_u32_e32 v118, v9, v6
	v_min_u32_e32 v119, v4, v2
	v_max3_u32 v2, v91, v4, v2
	v_max3_u32 v4, v92, v9, v6
	v_max3_u32 v5, v93, v5, v7
	v_max3_u32 v6, v95, v17, v50
	v_max3_u32 v7, v96, v10, v13
	v_max3_u32 v9, v98, v15, v11
	v_max3_u32 v10, v99, v12, v14
	v_max3_u32 v8, v101, v8, v16
	v_max_u32_e32 v11, v83, v119
	v_max_u32_e32 v12, v84, v118
	v_max_u32_e32 v13, v85, v117
	v_max_u32_e32 v14, v86, v116
	v_max_u32_e32 v15, v87, v53
	v_max_u32_e32 v16, v88, v52
	v_max_u32_e32 v17, v89, v51
	v_max_u32_e32 v3, v90, v3
	v_max_u32_e32 v50, v2, v7
	v_min_u32_e32 v2, v2, v7
	v_max_u32_e32 v7, v4, v9
	v_min_u32_e32 v4, v4, v9
	v_max_u32_e32 v9, v5, v10
	v_min_u32_e32 v5, v5, v10
	v_max_u32_e32 v10, v6, v8
	v_min_u32_e32 v6, v6, v8
	v_max_u32_e32 v8, v11, v15
	v_min_u32_e32 v11, v11, v15
	v_max_u32_e32 v15, v12, v16
	v_min_u32_e32 v12, v12, v16
	v_max_u32_e32 v16, v13, v17
	v_min_u32_e32 v13, v13, v17
	v_max_u32_e32 v17, v14, v3
	v_min_u32_e32 v3, v14, v3
	v_max_u32_e32 v14, v50, v9
	v_min_u32_e32 v9, v50, v9
	v_max_u32_e32 v50, v7, v10
	v_min_u32_e32 v7, v7, v10
	v_max_u32_e32 v10, v2, v5
	v_min_u32_e32 v2, v2, v5
	v_max_u32_e32 v5, v4, v6
	v_min_u32_e32 v4, v4, v6
	v_max_u32_e32 v6, v8, v16
	v_min_u32_e32 v8, v8, v16
	v_max_u32_e32 v16, v15, v17
	v_min_u32_e32 v15, v15, v17
	v_max_u32_e32 v17, v11, v13
	v_min_u32_e32 v11, v11, v13
	v_max_u32_e32 v13, v12, v3
	v_min_u32_e32 v3, v12, v3
	v_max_u32_e32 v12, v14, v50
	v_min_u32_e32 v14, v14, v50
	v_max_u32_e32 v50, v9, v7
	v_min_u32_e32 v7, v9, v7
	v_max_u32_e32 v9, v10, v5
	v_min_u32_e32 v5, v10, v5
	v_max_u32_e32 v10, v2, v4
	v_min_u32_e32 v2, v2, v4
	v_max_u32_e32 v4, v6, v16
	v_min_u32_e32 v6, v6, v16
	v_max_u32_e32 v16, v8, v15
	v_min_u32_e32 v8, v8, v15
	v_max_u32_e32 v15, v17, v13
	v_min_u32_e32 v13, v17, v13
	v_max_u32_e32 v17, v11, v3
	v_min_u32_e32 v3, v11, v3
	v_max_u32_e32 v83, v4, v12
	v_min_u32_e32 v91, v4, v12
	v_max_u32_e32 v84, v6, v14
	v_min_u32_e32 v92, v6, v14
	v_max_u32_e32 v85, v16, v50
	v_min_u32_e32 v93, v16, v50
	v_max_u32_e32 v86, v8, v7
	v_min_u32_e32 v95, v8, v7
	v_max_u32_e32 v87, v15, v9
	v_min_u32_e32 v96, v15, v9
	v_max_u32_e32 v88, v13, v5
	v_min_u32_e32 v98, v13, v5
	v_max_u32_e32 v89, v17, v10
	v_min_u32_e32 v99, v17, v10
	v_max_u32_e32 v90, v3, v2
	v_min_u32_e32 v101, v3, v2
	s_cbranch_scc1 .LBB0_134
; __device__ __forceinline__ float unordf(unsigned v) { return __uint_as_float(v ^ ((~(unsigned)((int)v >> 31)) | 0x80000000u)); }
; __device__ __forceinline__ void route_half(const unsigned char* kp, const bf16* qptr, int r, int hf, unsigned (&L)[16]) {
;     ...
;     for (int j = 0; j < 16; ++j) pk[j] = (unsigned)__shfl_xor((int)L[j], 32);
;     merge16_desc(L, pk);
; __device__ __forceinline__ void phase_route(CArgs& A, int l, unsigned char* lds, int tid) {
;     ...
;         for (int j = 0; j < 16; ++j) { v1[j] = unordf(L1[j] & ~0x7Fu); v2[j] = unordf(L2[j] & ~0x7Fu); L3[j] = 0u; }
	v_max_u32_e32 v2, v67, v114
	v_max_u32_e32 v3, v68, v113
	v_max_u32_e32 v4, v69, v112
	v_max_u32_e32 v5, v70, v111
	v_max_u32_e32 v6, v71, v110
	v_max_u32_e32 v7, v72, v109
	v_max_u32_e32 v8, v73, v108
	v_max_u32_e32 v9, v74, v107
	v_max_u32_e32 v10, v75, v106
	v_max_u32_e32 v11, v76, v105
	v_max_u32_e32 v12, v77, v104
	v_max_u32_e32 v13, v78, v103
	v_max_u32_e32 v14, v79, v102
	v_max_u32_e32 v15, v80, v100
	v_max_u32_e32 v16, v81, v97
	v_max_u32_e32 v17, v82, v94
	v_max_u32_e32 v18, v2, v10
	v_min_u32_e32 v2, v2, v10
	v_max_u32_e32 v10, v3, v11
	v_min_u32_e32 v3, v3, v11
	v_max_u32_e32 v11, v4, v12
	v_min_u32_e32 v4, v4, v12
	v_max_u32_e32 v12, v5, v13
	v_min_u32_e32 v5, v5, v13
	v_max_u32_e32 v13, v6, v14
	v_min_u32_e32 v6, v6, v14
	v_max_u32_e32 v14, v7, v15
	v_min_u32_e32 v7, v7, v15
	v_max_u32_e32 v15, v8, v16
	v_min_u32_e32 v8, v8, v16
	v_max_u32_e32 v16, v9, v17
	v_min_u32_e32 v9, v9, v17
	v_max_u32_e32 v17, v18, v13
	v_min_u32_e32 v13, v18, v13
	v_max_u32_e32 v18, v10, v14
	v_min_u32_e32 v10, v10, v14
	v_max_u32_e32 v14, v11, v15
	v_min_u32_e32 v11, v11, v15
	v_max_u32_e32 v15, v12, v16
	v_min_u32_e32 v12, v12, v16
	v_max_u32_e32 v16, v2, v6
	v_min_u32_e32 v2, v2, v6
	v_max_u32_e32 v6, v3, v7
	v_min_u32_e32 v3, v3, v7
	v_max_u32_e32 v7, v4, v8
	v_min_u32_e32 v4, v4, v8
	v_max_u32_e32 v8, v5, v9
	v_min_u32_e32 v5, v5, v9
	v_max_u32_e32 v9, v17, v14
	v_min_u32_e32 v14, v17, v14
	v_max_u32_e32 v17, v18, v15
	v_min_u32_e32 v15, v18, v15
	v_max_u32_e32 v18, v13, v11
	v_min_u32_e32 v11, v13, v11
	v_max_u32_e32 v13, v10, v12
	v_min_u32_e32 v10, v10, v12
	v_max_u32_e32 v12, v16, v7
	v_min_u32_e32 v16, v16, v7
	v_max_u32_e32 v19, v6, v8
	v_min_u32_e32 v6, v6, v8
	v_max_u32_e32 v20, v2, v4
	v_min_u32_e32 v2, v2, v4
	v_max_u32_e32 v21, v3, v5
	v_min_u32_e32 v3, v3, v5
	v_max_u32_e32 v4, v9, v17
	v_max_u32_e32 v5, v14, v15
	v_max_u32_e32 v7, v18, v13
	v_max_u32_e32 v8, v11, v10
	v_max_u32_e32 v53, v12, v19
	v_max_u32_e32 v51, v16, v6
	v_max_u32_e32 v49, v20, v21
	v_max_u32_e32 v47, v2, v3
	v_min_u32_e32 v9, v9, v17
	v_min_u32_e32 v69, v14, v15
	v_min_u32_e32 v67, v18, v13
	v_min_u32_e32 v68, v11, v10
	v_min_u32_e32 v52, v12, v19
	v_min_u32_e32 v50, v16, v6
	v_min_u32_e32 v48, v20, v21
	v_min_u32_e32 v46, v2, v3
	ds_bpermute_b32 v2, v64, v83
	ds_bpermute_b32 v3, v64, v91
	ds_bpermute_b32 v6, v64, v84
	ds_bpermute_b32 v10, v64, v92
	ds_bpermute_b32 v11, v64, v85
	ds_bpermute_b32 v12, v64, v93
	ds_bpermute_b32 v13, v64, v86
	ds_bpermute_b32 v14, v64, v95
	ds_bpermute_b32 v15, v64, v87
	ds_bpermute_b32 v16, v64, v96
	ds_bpermute_b32 v17, v64, v88
	ds_bpermute_b32 v18, v64, v101
	ds_bpermute_b32 v19, v64, v90
	ds_bpermute_b32 v20, v64, v99
	ds_bpermute_b32 v21, v64, v89
	ds_bpermute_b32 v22, v64, v98
	s_waitcnt lgkmcnt(4)
	v_max_u32_e32 v18, v83, v18
	s_waitcnt lgkmcnt(3)
	v_max_u32_e32 v19, v91, v19
	s_waitcnt lgkmcnt(2)
	v_max_u32_e32 v20, v84, v20
	s_waitcnt lgkmcnt(1)
	v_max_u32_e32 v21, v92, v21
	s_waitcnt lgkmcnt(0)
	v_max_u32_e32 v22, v85, v22
	v_max_u32_e32 v17, v93, v17
	v_max_u32_e32 v16, v86, v16
	v_max_u32_e32 v15, v95, v15
	v_max_u32_e32 v14, v87, v14
	v_max_u32_e32 v13, v96, v13
	v_max_u32_e32 v12, v88, v12
	v_max_u32_e32 v11, v98, v11
	v_max_u32_e32 v10, v89, v10
	v_max_u32_e32 v6, v99, v6
	v_max_u32_e32 v3, v90, v3
	v_max_u32_e32 v2, v101, v2
	v_max_u32_e32 v23, v18, v14
	v_min_u32_e32 v14, v18, v14
	v_max_u32_e32 v18, v19, v13
	v_min_u32_e32 v13, v19, v13
	v_max_u32_e32 v19, v20, v12
	v_min_u32_e32 v12, v20, v12
	v_max_u32_e32 v20, v21, v11
	v_min_u32_e32 v11, v21, v11
	v_max_u32_e32 v21, v22, v10
	v_min_u32_e32 v10, v22, v10
	v_max_u32_e32 v22, v17, v6
	v_min_u32_e32 v6, v17, v6
	v_max_u32_e32 v17, v16, v3
	v_min_u32_e32 v3, v16, v3
	v_max_u32_e32 v16, v15, v2
	v_min_u32_e32 v2, v15, v2
	v_max_u32_e32 v15, v23, v21
	v_min_u32_e32 v21, v23, v21
	v_max_u32_e32 v23, v18, v22
	v_min_u32_e32 v18, v18, v22
	v_max_u32_e32 v22, v19, v17
	v_min_u32_e32 v17, v19, v17
	v_max_u32_e32 v19, v20, v16
	v_min_u32_e32 v16, v20, v16
	v_max_u32_e32 v20, v14, v10
	v_min_u32_e32 v10, v14, v10
	v_max_u32_e32 v14, v13, v6
	v_min_u32_e32 v6, v13, v6
	v_max_u32_e32 v13, v12, v3
	v_min_u32_e32 v3, v12, v3
	v_max_u32_e32 v12, v11, v2
	v_min_u32_e32 v2, v11, v2
	v_max_u32_e32 v11, v15, v22
	v_min_u32_e32 v15, v15, v22
	v_max_u32_e32 v22, v23, v19
	v_min_u32_e32 v19, v23, v19
	v_max_u32_e32 v23, v21, v17
	v_min_u32_e32 v17, v21, v17
	v_max_u32_e32 v21, v18, v16
	v_min_u32_e32 v16, v18, v16
	v_max_u32_e32 v18, v20, v13
	v_min_u32_e32 v13, v20, v13
	v_max_u32_e32 v20, v14, v12
	v_min_u32_e32 v12, v14, v12
	v_max_u32_e32 v14, v10, v3
	v_min_u32_e32 v3, v10, v3
	v_max_u32_e32 v10, v6, v2
	v_min_u32_e32 v2, v6, v2
	v_cmp_lt_i32_e32 vcc, -1, v4
	v_max_u32_e32 v45, v11, v22
	v_min_u32_e32 v44, v11, v22
	v_max_u32_e32 v11, v3, v2
	v_min_u32_e32 v6, v3, v2
	v_cndmask_b32_e64 v2, v182, -1, vcc
	v_cmp_lt_i32_e32 vcc, -1, v9
	v_max_u32_e32 v35, v13, v12
	v_min_u32_e32 v34, v13, v12
	v_bitop3_b32 v12, v2, v4, s81 bitop3:0x78
	v_cndmask_b32_e64 v2, v182, -1, vcc
	v_cmp_lt_i32_e32 vcc, -1, v44
	v_max_u32_e32 v43, v15, v19
	v_bitop3_b32 v13, v2, v9, s81 bitop3:0x78
	v_cndmask_b32_e64 v2, v182, -1, vcc
	v_cmp_lt_i32_e32 vcc, -1, v5
	v_max_u32_e32 v33, v14, v10
	v_min_u32_e32 v32, v14, v10
	v_bitop3_b32 v14, v2, v44, s81 bitop3:0x78
	v_cndmask_b32_e64 v2, v182, -1, vcc
	v_cmp_lt_i32_e32 vcc, -1, v43
	v_min_u32_e32 v42, v15, v19
	v_bitop3_b32 v15, v2, v5, s81 bitop3:0x78
	v_cndmask_b32_e64 v2, v182, -1, vcc
	v_cmp_lt_i32_e32 vcc, -1, v69
	v_max_u32_e32 v39, v17, v16
	v_min_u32_e32 v38, v17, v16
	v_bitop3_b32 v16, v2, v43, s81 bitop3:0x78
	v_cndmask_b32_e64 v2, v182, -1, vcc
; __device__ __forceinline__ unsigned ordf(float f) { unsigned u = __float_as_uint(f); return u ^ ((unsigned)((int)u >> 31) | 0x80000000u); }
; __device__ __forceinline__ float unordf(unsigned v) { return __uint_as_float(v ^ ((~(unsigned)((int)v >> 31)) | 0x80000000u)); }
; __device__ __forceinline__ void phase_route(CArgs& A, int l, unsigned char* lds, int tid) {
;     ...
;         for (int j = 0; j < 16; ++j) { v1[j] = unordf(L1[j] & ~0x7Fu); v2[j] = unordf(L2[j] & ~0x7Fu); L3[j] = 0u; }
;         {
;             constexpr CandTab CT = make_cand();
;             unsigned g1[16], g2[16];
; #pragma unroll
;             for (int k = 0; k < 16; ++k) {
;                 L3[k] = (ordf(v1[CT.i[k]] + v2[CT.j[k]]) & ~0xFFu) | (unsigned)(CT.i[k] * 16 + CT.j[k]);
;                 g1[k] = (ordf(v1[CT.i[16 + k]] + v2[CT.j[16 + k]]) & ~0xFFu) | (unsigned)(CT.i[16 + k] * 16 + CT.j[16 + k]);
;                 g2[k] = (ordf(v1[CT.i[32 + k]] + v2[CT.j[32 + k]]) & ~0xFFu) | (unsigned)(CT.i[32 + k] * 16 + CT.j[32 + k]); }
	v_cmp_lt_i32_e32 vcc, -1, v42
	v_max_u32_e32 v41, v23, v21
	v_bitop3_b32 v17, v2, v69, s81 bitop3:0x78
	v_cndmask_b32_e64 v2, v182, -1, vcc
	v_cmp_lt_i32_e32 vcc, -1, v7
	v_max_u32_e32 v37, v18, v20
	v_min_u32_e32 v36, v18, v20
	v_bitop3_b32 v18, v2, v42, s81 bitop3:0x78
	v_cndmask_b32_e64 v2, v182, -1, vcc
	v_cmp_lt_i32_e32 vcc, -1, v41
	v_min_u32_e32 v40, v23, v21
	v_bitop3_b32 v19, v2, v7, s81 bitop3:0x78
	v_cndmask_b32_e64 v2, v182, -1, vcc
	v_cmp_lt_i32_e32 vcc, -1, v67
	v_bitop3_b32 v20, v2, v41, s81 bitop3:0x78
	v_and_b32_e32 v78, 0xffffff80, v46
	v_cndmask_b32_e64 v2, v182, -1, vcc
	v_cmp_lt_i32_e32 vcc, -1, v40
	v_bitop3_b32 v21, v2, v67, s81 bitop3:0x78
	s_brev_b32 s0, 1
	v_cndmask_b32_e64 v2, v182, -1, vcc
	v_cmp_lt_i32_e32 vcc, -1, v8
	v_bitop3_b32 v22, v2, v40, s81 bitop3:0x78
	v_and_b32_e32 v40, 0x7f, v40
	v_cndmask_b32_e64 v2, v182, -1, vcc
	v_cmp_lt_i32_e32 vcc, -1, v39
	v_bitop3_b32 v23, v2, v8, s81 bitop3:0x78
	v_and_b32_e32 v41, 0x7f, v41
	v_cndmask_b32_e64 v2, v182, -1, vcc
	v_cmp_lt_i32_e32 vcc, -1, v68
	v_bitop3_b32 v24, v2, v39, s81 bitop3:0x78
	v_and_b32_e32 v39, 0x7f, v39
	v_cndmask_b32_e64 v2, v182, -1, vcc
	v_cmp_lt_i32_e32 vcc, -1, v38
	v_bitop3_b32 v25, v2, v68, s81 bitop3:0x78
	v_and_b32_e32 v42, 0x7f, v42
	v_cndmask_b32_e64 v2, v182, -1, vcc
	v_cmp_lt_i32_e32 vcc, -1, v53
	v_bitop3_b32 v26, v2, v38, s81 bitop3:0x78
	v_and_b32_e32 v38, 0x7f, v38
	v_cndmask_b32_e64 v2, v182, -1, vcc
	v_cmp_lt_i32_e32 vcc, -1, v37
	v_bitop3_b32 v27, v2, v53, s81 bitop3:0x78
	v_and_b32_e32 v43, 0x7f, v43
	v_cndmask_b32_e64 v2, v182, -1, vcc
	v_cmp_lt_i32_e32 vcc, -1, v52
	v_bitop3_b32 v28, v2, v37, s81 bitop3:0x78
	v_and_b32_e32 v37, 0x7f, v37
	v_cndmask_b32_e64 v2, v182, -1, vcc
	v_cmp_lt_i32_e32 vcc, -1, v36
	v_bitop3_b32 v29, v2, v52, s81 bitop3:0x78
	v_and_b32_e32 v44, 0x7f, v44
	v_cndmask_b32_e64 v2, v182, -1, vcc
	v_cmp_lt_i32_e32 vcc, -1, v51
	v_bitop3_b32 v30, v2, v36, s81 bitop3:0x78
	v_add_f32_e32 v30, v12, v30
	v_cndmask_b32_e64 v2, v182, -1, vcc
	v_cmp_lt_i32_e32 vcc, -1, v35
	v_bitop3_b32 v31, v2, v51, s81 bitop3:0x78
	v_and_b32_e32 v36, 0x7f, v36
	v_cndmask_b32_e64 v2, v182, -1, vcc
	v_cmp_lt_i32_e32 vcc, -1, v50
	v_bitop3_b32 v70, v2, v35, s81 bitop3:0x78
	v_add_f32_e32 v70, v12, v70
	v_cndmask_b32_e64 v2, v182, -1, vcc
	v_cmp_lt_i32_e32 vcc, -1, v34
	v_bitop3_b32 v71, v2, v50, s81 bitop3:0x78
	v_and_b32_e32 v35, 0x7f, v35
	v_cndmask_b32_e64 v2, v182, -1, vcc
	v_cmp_lt_i32_e32 vcc, -1, v49
	v_bitop3_b32 v72, v2, v34, s81 bitop3:0x78
	v_add_f32_e32 v72, v12, v72
	v_cndmask_b32_e64 v2, v182, -1, vcc
	v_cmp_lt_i32_e32 vcc, -1, v33
	v_bitop3_b32 v73, v2, v49, s81 bitop3:0x78
	v_and_b32_e32 v34, 0x7f, v34
	v_cndmask_b32_e64 v2, v182, -1, vcc
	v_cmp_lt_i32_e32 vcc, -1, v48
	v_bitop3_b32 v74, v2, v33, s81 bitop3:0x78
	v_add_f32_e32 v74, v12, v74
	v_cndmask_b32_e64 v2, v182, -1, vcc
	v_cmp_lt_i32_e32 vcc, -1, v32
	v_bitop3_b32 v75, v2, v48, s81 bitop3:0x78
	v_and_b32_e32 v33, 0x7f, v33
	v_cndmask_b32_e64 v2, v182, -1, vcc
	v_cmp_lt_i32_e32 vcc, -1, v47
	v_bitop3_b32 v76, v2, v32, s81 bitop3:0x78
	v_and_b32_e32 v32, 0x7f, v32
	v_cndmask_b32_e64 v2, v182, -1, vcc
	v_cmp_lt_i32_e32 vcc, -1, v11
	v_bitop3_b32 v10, v2, v47, s81 bitop3:0x78
	v_and_b32_e32 v47, 0x7f, v47
	v_cndmask_b32_e64 v2, v182, -1, vcc
	v_cmp_lt_i32_e32 vcc, -1, v46
	v_bitop3_b32 v77, v2, v11, s81 bitop3:0x78
	v_and_b32_e32 v2, 0xffffff80, v45
	v_cndmask_b32_e64 v79, v182, -1, vcc
	v_cmp_lt_i32_e32 vcc, -1, v45
	v_add_f32_e32 v77, v12, v77
	v_and_b32_e32 v11, 0x7f, v11
	v_cndmask_b32_e64 v3, v182, -1, vcc
	v_xor_b32_e32 v3, v3, v2
	v_xor_b32_e32 v2, v79, v78
	v_add_f32_e32 v79, v3, v12
	v_ashrrev_i32_e32 v80, 31, v79
	v_or_b32_e32 v80, 0x80000000, v80
	v_bitop3_b32 v79, v80, s82, v79 bitop3:0x48
	v_add_f32_e32 v80, v3, v13
	v_ashrrev_i32_e32 v81, 31, v80
	v_bitop3_b32 v80, v81, v80, s0 bitop3:0x36
	v_add_f32_e32 v81, v17, v18
	v_ashrrev_i32_e32 v82, 31, v81
	v_bitop3_b32 v81, v82, v81, s0 bitop3:0x36
	v_add_f32_e32 v82, v12, v14
	v_ashrrev_i32_e32 v83, 31, v82
	v_bitop3_b32 v82, v83, v82, s0 bitop3:0x36
	v_add_f32_e32 v83, v13, v14
	v_ashrrev_i32_e32 v84, 31, v83
	v_bitop3_b32 v83, v84, v83, s0 bitop3:0x36
	v_add_f32_e32 v84, v3, v19
	v_ashrrev_i32_e32 v85, 31, v84
	v_bitop3_b32 v84, v85, v84, s0 bitop3:0x36
	v_add_f32_e32 v85, v12, v16
	v_ashrrev_i32_e32 v86, 31, v85
	v_bitop3_b32 v85, v86, v85, s0 bitop3:0x36
	v_add_f32_e32 v86, v13, v16
	v_ashrrev_i32_e32 v87, 31, v86
	v_bitop3_b32 v86, v87, v86, s0 bitop3:0x36
	v_add_f32_e32 v87, v19, v14
	v_ashrrev_i32_e32 v88, 31, v87
	v_or_b32_e32 v88, 0x80000000, v88
	v_bitop3_b32 v87, v88, s82, v87 bitop3:0x48
	v_add_f32_e32 v88, v12, v18
	v_ashrrev_i32_e32 v89, 31, v88
	v_bitop3_b32 v88, v89, v88, s0 bitop3:0x36
	v_add_f32_e32 v89, v13, v18
	v_ashrrev_i32_e32 v90, 31, v89
	v_add_f32_e32 v19, v19, v16
	v_bitop3_b32 v89, v90, v89, s0 bitop3:0x36
	v_ashrrev_i32_e32 v90, 31, v19
	v_or_b32_e32 v90, 0x80000000, v90
	v_bitop3_b32 v19, v90, s82, v19 bitop3:0x48
	v_add_f32_e32 v90, v12, v20
	v_ashrrev_i32_e32 v91, 31, v90
	v_bitop3_b32 v90, v91, v90, s0 bitop3:0x36
	v_add_f32_e32 v91, v13, v20
	v_ashrrev_i32_e32 v92, 31, v91
	v_bitop3_b32 v91, v92, v91, s0 bitop3:0x36
	v_add_f32_e32 v92, v3, v21
	v_ashrrev_i32_e32 v93, 31, v92
	v_or_b32_e32 v93, 0x80000000, v93
	v_bitop3_b32 v92, v93, s82, v92 bitop3:0x48
	v_add_f32_e32 v93, v12, v22
	v_ashrrev_i32_e32 v94, 31, v93
	v_add_f32_e32 v22, v13, v22
	v_bitop3_b32 v93, v94, v93, s0 bitop3:0x36
	v_ashrrev_i32_e32 v94, 31, v22
	v_add_f32_e32 v21, v21, v14
	v_bitop3_b32 v22, v94, v22, s0 bitop3:0x36
	v_ashrrev_i32_e32 v94, 31, v21
	v_or_b32_e32 v94, 0x80000000, v94
; __device__ __forceinline__ unsigned ordf(float f) { unsigned u = __float_as_uint(f); return u ^ ((unsigned)((int)u >> 31) | 0x80000000u); }
; __device__ __forceinline__ void phase_route(CArgs& A, int l, unsigned char* lds, int tid) {
;     ...
;                 L3[k] = (ordf(v1[CT.i[k]] + v2[CT.j[k]]) & ~0xFFu) | (unsigned)(CT.i[k] * 16 + CT.j[k]);
;                 g1[k] = (ordf(v1[CT.i[16 + k]] + v2[CT.j[16 + k]]) & ~0xFFu) | (unsigned)(CT.i[16 + k] * 16 + CT.j[16 + k]);
;                 g2[k] = (ordf(v1[CT.i[32 + k]] + v2[CT.j[32 + k]]) & ~0xFFu) | (unsigned)(CT.i[32 + k] * 16 + CT.j[32 + k]); }
;             sort16_desc(L3); sort16_desc(g1); sort16_desc(g2); merge16_desc(L3, g1); merge16_desc(L3, g2);
	v_bitop3_b32 v21, v94, s82, v21 bitop3:0x48
	v_add_f32_e32 v94, v12, v24
	v_ashrrev_i32_e32 v95, 31, v94
	v_add_f32_e32 v24, v13, v24
	v_bitop3_b32 v94, v95, v94, s0 bitop3:0x36
	v_ashrrev_i32_e32 v95, 31, v24
	v_bitop3_b32 v24, v95, v24, s0 bitop3:0x36
	v_add_f32_e32 v95, v3, v23
	v_ashrrev_i32_e32 v96, 31, v95
	v_or_b32_e32 v96, 0x80000000, v96
	v_add_f32_e32 v13, v13, v26
	v_bitop3_b32 v95, v96, s82, v95 bitop3:0x48
	v_add_f32_e32 v96, v12, v26
	v_ashrrev_i32_e32 v26, 31, v13
	v_add_f32_e32 v23, v23, v14
	v_bitop3_b32 v13, v26, v13, s0 bitop3:0x36
	v_ashrrev_i32_e32 v26, 31, v23
	v_or_b32_e32 v26, 0x80000000, v26
	v_bitop3_b32 v23, v26, s82, v23 bitop3:0x48
	v_add_f32_e32 v26, v12, v28
	v_ashrrev_i32_e32 v28, 31, v26
	v_ashrrev_i32_e32 v97, 31, v96
	v_bitop3_b32 v26, v28, v26, s0 bitop3:0x36
	v_add_f32_e32 v28, v3, v15
	v_bitop3_b32 v96, v97, v96, s0 bitop3:0x36
	v_ashrrev_i32_e32 v97, 31, v28
	v_bitop3_b32 v28, v97, v28, s0 bitop3:0x36
	v_add_f32_e32 v97, v3, v25
	v_ashrrev_i32_e32 v98, 31, v97
	v_or_b32_e32 v98, 0x80000000, v98
	v_bitop3_b32 v97, v98, s82, v97 bitop3:0x48
	v_ashrrev_i32_e32 v98, 31, v30
	v_bitop3_b32 v30, v98, v30, s0 bitop3:0x36
	v_add_f32_e32 v98, v15, v14
	v_ashrrev_i32_e32 v99, 31, v98
	v_add_f32_e32 v25, v25, v14
	v_bitop3_b32 v98, v99, v98, s0 bitop3:0x36
	v_ashrrev_i32_e32 v99, 31, v25
	v_or_b32_e32 v99, 0x80000000, v99
	v_bitop3_b32 v25, v99, s82, v25 bitop3:0x48
	v_ashrrev_i32_e32 v99, 31, v70
	v_bitop3_b32 v70, v99, v70, s0 bitop3:0x36
	v_add_f32_e32 v99, v15, v16
	v_ashrrev_i32_e32 v100, 31, v99
	v_add_f32_e32 v27, v3, v27
	v_add_f32_e32 v18, v15, v18
	v_add_f32_e32 v15, v15, v20
	v_bitop3_b32 v99, v100, v99, s0 bitop3:0x36
	v_ashrrev_i32_e32 v100, 31, v27
	v_ashrrev_i32_e32 v20, 31, v15
	v_or_b32_e32 v100, 0x80000000, v100
	v_bitop3_b32 v15, v20, v15, s0 bitop3:0x36
	v_add_f32_e32 v20, v3, v31
	v_bitop3_b32 v27, v100, s82, v27 bitop3:0x48
	v_ashrrev_i32_e32 v100, 31, v72
	v_ashrrev_i32_e32 v31, 31, v20
	v_bitop3_b32 v72, v100, v72, s0 bitop3:0x36
	v_ashrrev_i32_e32 v100, 31, v18
	v_add_f32_e32 v29, v3, v29
	v_or_b32_e32 v31, 0x80000000, v31
	v_bitop3_b32 v18, v100, v18, s0 bitop3:0x36
	v_ashrrev_i32_e32 v100, 31, v29
	v_bitop3_b32 v20, v31, s82, v20 bitop3:0x48
	v_add_f32_e32 v31, v12, v76
	v_or_b32_e32 v100, 0x80000000, v100
	v_ashrrev_i32_e32 v76, 31, v31
	v_bitop3_b32 v29, v100, s82, v29 bitop3:0x48
	v_ashrrev_i32_e32 v100, 31, v74
	v_bitop3_b32 v31, v76, v31, s0 bitop3:0x36
	v_add_f32_e32 v76, v3, v17
	v_cmp_lt_i32_e32 vcc, -1, v6
	v_bitop3_b32 v74, v100, v74, s0 bitop3:0x36
	v_ashrrev_i32_e32 v100, 31, v76
	v_add_f32_e32 v71, v3, v71
	v_cndmask_b32_e64 v78, v182, -1, vcc
	v_bitop3_b32 v76, v100, v76, s0 bitop3:0x36
	v_ashrrev_i32_e32 v100, 31, v71
	v_bitop3_b32 v78, v78, v6, s81 bitop3:0x78
	v_or_b32_e32 v100, 0x80000000, v100
	v_add_f32_e32 v16, v17, v16
	v_bitop3_b32 v71, v100, s82, v71 bitop3:0x48
	v_ashrrev_i32_e32 v100, 31, v77
	v_add_f32_e32 v14, v17, v14
	v_add_f32_e32 v12, v12, v78
	v_ashrrev_i32_e32 v17, 31, v16
	v_bitop3_b32 v77, v100, v77, s0 bitop3:0x36
	v_ashrrev_i32_e32 v100, 31, v14
	v_ashrrev_i32_e32 v78, 31, v12
	v_bitop3_b32 v16, v17, v16, s0 bitop3:0x36
	v_add_f32_e32 v17, v3, v75
	v_bitop3_b32 v14, v100, v14, s0 bitop3:0x36
	v_bitop3_b32 v12, v78, v12, s0 bitop3:0x36
	v_ashrrev_i32_e32 v75, 31, v17
	v_and_or_b32 v80, v80, s82, 16
	v_and_or_b32 v82, v82, s82, 1
	v_and_or_b32 v83, v83, s82, 17
	v_and_or_b32 v85, v85, s82, 2
	v_and_or_b32 v86, v86, s82, 18
	v_and_or_b32 v88, v88, s82, 3
	v_and_or_b32 v89, v89, s82, 19
	v_and_or_b32 v90, v90, s82, 4
	v_and_or_b32 v91, v91, s82, 20
	v_and_or_b32 v93, v93, s82, 5
	v_and_or_b32 v22, v22, s82, 21
	v_and_or_b32 v94, v94, s82, 6
	v_and_or_b32 v24, v24, s82, 22
	v_and_or_b32 v96, v96, s82, 7
	v_and_or_b32 v13, v13, s82, 23
	v_and_or_b32 v26, v26, s82, 8
	v_and_or_b32 v28, v28, s82, 32
	v_and_or_b32 v30, v30, s82, 9
	v_and_or_b32 v98, v98, s82, 33
	v_and_or_b32 v70, v70, s82, 10
	v_and_or_b32 v99, v99, s82, 34
	v_and_or_b32 v72, v72, s82, 11
	v_and_or_b32 v18, v18, s82, 35
	v_and_or_b32 v74, v74, s82, 12
	v_and_or_b32 v15, v15, s82, 36
	v_and_or_b32 v31, v31, s82, 13
	v_and_or_b32 v76, v76, s82, 48
	v_and_or_b32 v77, v77, s82, 14
	v_and_or_b32 v14, v14, s82, 49
	v_and_or_b32 v12, v12, s82, 15
	v_and_or_b32 v16, v16, s82, 50
	v_or_b32_e32 v75, 0x80000000, v75
	v_add_f32_e32 v73, v3, v73
	v_bitop3_b32 v17, v75, s82, v17 bitop3:0x48
	v_max_u32_e32 v75, v79, v82
	v_min_u32_e32 v78, v79, v82
	v_max_u32_e32 v79, v88, v85
	v_min_u32_e32 v82, v88, v85
	v_max_u32_e32 v85, v90, v93
	v_min_u32_e32 v88, v90, v93
	v_max_u32_e32 v90, v96, v94
	v_min_u32_e32 v93, v96, v94
	v_max_u32_e32 v94, v26, v30
	v_min_u32_e32 v26, v26, v30
	v_max_u32_e32 v30, v72, v70
	v_min_u32_e32 v70, v72, v70
	v_max_u32_e32 v72, v74, v31
	v_min_u32_e32 v31, v74, v31
	v_max_u32_e32 v74, v12, v77
	v_min_u32_e32 v12, v12, v77
	v_max_u32_e32 v106, v80, v83
	v_min_u32_e32 v80, v80, v83
	v_max_u32_e32 v83, v89, v86
	v_min_u32_e32 v86, v89, v86
	v_max_u32_e32 v89, v91, v22
	v_min_u32_e32 v22, v91, v22
	v_max_u32_e32 v91, v13, v24
	v_min_u32_e32 v13, v13, v24
	v_max_u32_e32 v24, v28, v98
	v_min_u32_e32 v28, v28, v98
	v_max_u32_e32 v98, v18, v99
	v_min_u32_e32 v18, v18, v99
	v_max_u32_e32 v99, v15, v76
	v_min_u32_e32 v15, v15, v76
	v_max_u32_e32 v76, v16, v14
	v_min_u32_e32 v14, v16, v14
	v_ashrrev_i32_e32 v100, 31, v73
	v_max_u32_e32 v77, v75, v82
	v_min_u32_e32 v75, v75, v82
	v_max_u32_e32 v82, v78, v79
	v_min_u32_e32 v78, v78, v79
	v_max_u32_e32 v79, v93, v85
	v_min_u32_e32 v85, v93, v85
	v_max_u32_e32 v93, v90, v88
	v_min_u32_e32 v88, v90, v88
	v_max_u32_e32 v90, v94, v70
; __device__ __forceinline__ void phase_route(CArgs& A, int l, unsigned char* lds, int tid) {
;     ...
;             sort16_desc(L3); sort16_desc(g1); sort16_desc(g2); merge16_desc(L3, g1); merge16_desc(L3, g2);
	v_min_u32_e32 v70, v94, v70
	v_max_u32_e32 v94, v26, v30
	v_min_u32_e32 v26, v26, v30
	v_max_u32_e32 v30, v12, v72
	v_min_u32_e32 v12, v12, v72
	v_max_u32_e32 v72, v74, v31
	v_min_u32_e32 v31, v74, v31
	v_max_u32_e32 v16, v106, v86
	v_min_u32_e32 v86, v106, v86
	v_max_u32_e32 v106, v80, v83
	v_min_u32_e32 v80, v80, v83
	v_max_u32_e32 v83, v13, v89
	v_min_u32_e32 v13, v13, v89
	v_max_u32_e32 v89, v91, v22
	v_min_u32_e32 v22, v91, v22
	v_max_u32_e32 v91, v24, v18
	v_min_u32_e32 v18, v24, v18
	v_max_u32_e32 v24, v28, v98
	v_min_u32_e32 v28, v28, v98
	v_max_u32_e32 v98, v14, v99
	v_min_u32_e32 v14, v14, v99
	v_max_u32_e32 v99, v76, v15
	v_min_u32_e32 v15, v76, v15
	v_or_b32_e32 v100, 0x80000000, v100
	v_max_u32_e32 v74, v77, v82
	v_min_u32_e32 v77, v77, v82
	v_max_u32_e32 v82, v75, v78
	v_min_u32_e32 v75, v75, v78
	v_max_u32_e32 v78, v88, v85
	v_min_u32_e32 v85, v88, v85
	v_max_u32_e32 v88, v93, v79
	v_min_u32_e32 v79, v93, v79
	v_max_u32_e32 v93, v90, v94
	v_min_u32_e32 v90, v90, v94
	v_max_u32_e32 v94, v70, v26
	v_min_u32_e32 v26, v70, v26
	v_max_u32_e32 v70, v31, v12
	v_min_u32_e32 v12, v31, v12
	v_max_u32_e32 v31, v72, v30
	v_min_u32_e32 v30, v72, v30
	v_max_u32_e32 v76, v16, v106
	v_min_u32_e32 v16, v16, v106
	v_max_u32_e32 v106, v86, v80
	v_min_u32_e32 v80, v86, v80
	v_max_u32_e32 v86, v22, v13
	v_min_u32_e32 v13, v22, v13
	v_max_u32_e32 v22, v89, v83
	v_min_u32_e32 v83, v89, v83
	v_max_u32_e32 v89, v91, v24
	v_min_u32_e32 v24, v91, v24
	v_max_u32_e32 v91, v18, v28
	v_min_u32_e32 v18, v18, v28
	v_max_u32_e32 v28, v15, v14
	v_min_u32_e32 v14, v15, v14
	v_max_u32_e32 v15, v99, v98
	v_min_u32_e32 v98, v99, v98
	v_bitop3_b32 v73, v100, s82, v73 bitop3:0x48
	v_max_u32_e32 v72, v74, v85
	v_min_u32_e32 v74, v74, v85
	v_max_u32_e32 v85, v77, v78
	v_min_u32_e32 v77, v77, v78
	v_max_u32_e32 v78, v82, v79
	v_min_u32_e32 v79, v82, v79
	v_max_u32_e32 v82, v75, v88
	v_min_u32_e32 v75, v75, v88
	v_max_u32_e32 v88, v12, v93
	v_min_u32_e32 v12, v12, v93
	v_max_u32_e32 v93, v70, v90
	v_min_u32_e32 v70, v70, v90
	v_max_u32_e32 v90, v30, v94
	v_min_u32_e32 v30, v30, v94
	v_max_u32_e32 v94, v31, v26
	v_min_u32_e32 v26, v31, v26
	v_max_u32_e32 v99, v76, v13
	v_min_u32_e32 v13, v76, v13
	v_max_u32_e32 v76, v16, v86
	v_min_u32_e32 v16, v16, v86
	v_max_u32_e32 v86, v106, v83
	v_min_u32_e32 v83, v106, v83
	v_max_u32_e32 v106, v80, v22
	v_min_u32_e32 v22, v80, v22
	v_max_u32_e32 v80, v14, v89
	v_min_u32_e32 v14, v14, v89
	v_max_u32_e32 v89, v28, v24
	v_min_u32_e32 v24, v28, v24
	v_max_u32_e32 v28, v98, v91
	v_min_u32_e32 v91, v98, v91
	v_max_u32_e32 v98, v15, v18
	v_min_u32_e32 v15, v15, v18
	v_and_or_b32 v81, v81, s82, 51
	v_and_or_b32 v84, v84, s82, 64
	v_or_b32_e32 v87, 0x41, v87
	v_or_b32_e32 v19, 0x42, v19
	v_or_b32_e32 v92, 0x50, v92
	v_or_b32_e32 v21, 0x51, v21
	v_or_b32_e32 v95, 0x60, v95
	v_or_b32_e32 v23, 0x61, v23
	v_or_b32_e32 v97, 0x70, v97
	v_or_b32_e32 v25, 0x71, v25
	v_or_b32_e32 v27, 0x80, v27
	v_or_b32_e32 v29, 0x90, v29
	v_or_b32_e32 v20, 0xa0, v20
	v_or_b32_e32 v71, 0xb0, v71
	v_or_b32_e32 v73, 0xc0, v73
	v_or_b32_e32 v17, 0xd0, v17
	v_max_u32_e32 v31, v72, v78
	v_min_u32_e32 v72, v72, v78
	v_max_u32_e32 v78, v85, v82
	v_min_u32_e32 v82, v85, v82
	v_max_u32_e32 v85, v74, v79
	v_min_u32_e32 v74, v74, v79
	v_max_u32_e32 v79, v77, v75
	v_min_u32_e32 v75, v77, v75
	v_max_u32_e32 v77, v30, v12
	v_min_u32_e32 v12, v30, v12
	v_max_u32_e32 v30, v26, v70
	v_min_u32_e32 v26, v26, v70
	v_max_u32_e32 v70, v90, v88
	v_min_u32_e32 v88, v90, v88
	v_max_u32_e32 v90, v94, v93
	v_min_u32_e32 v93, v94, v93
	v_max_u32_e32 v18, v99, v86
	v_min_u32_e32 v86, v99, v86
	v_max_u32_e32 v99, v76, v106
	v_min_u32_e32 v76, v76, v106
	v_max_u32_e32 v106, v13, v83
	v_min_u32_e32 v13, v13, v83
	v_max_u32_e32 v83, v16, v22
	v_min_u32_e32 v16, v16, v22
	v_max_u32_e32 v22, v91, v14
	v_min_u32_e32 v14, v91, v14
	v_max_u32_e32 v91, v15, v24
	v_min_u32_e32 v15, v15, v24
	v_max_u32_e32 v24, v28, v80
	v_min_u32_e32 v28, v28, v80
	v_max_u32_e32 v80, v98, v89
	v_min_u32_e32 v89, v98, v89
	v_max_u32_e32 v94, v31, v78
	v_min_u32_e32 v31, v31, v78
	v_max_u32_e32 v78, v72, v82
	v_min_u32_e32 v72, v72, v82
	v_max_u32_e32 v82, v85, v79
	v_min_u32_e32 v79, v85, v79
	v_max_u32_e32 v85, v74, v75
	v_min_u32_e32 v74, v74, v75
	v_max_u32_e32 v75, v26, v12
	v_min_u32_e32 v12, v26, v12
	v_max_u32_e32 v26, v30, v77
	v_min_u32_e32 v30, v30, v77
	v_max_u32_e32 v77, v93, v88
	v_min_u32_e32 v88, v93, v88
	v_max_u32_e32 v93, v90, v70
	v_min_u32_e32 v70, v90, v70
	v_max_u32_e32 v98, v18, v99
	v_min_u32_e32 v18, v18, v99
	v_max_u32_e32 v99, v86, v76
	v_min_u32_e32 v76, v86, v76
	v_max_u32_e32 v86, v106, v83
	v_min_u32_e32 v83, v106, v83
	v_max_u32_e32 v106, v13, v16
	v_min_u32_e32 v13, v13, v16
	v_max_u32_e32 v16, v15, v14
	v_min_u32_e32 v14, v15, v14
	v_max_u32_e32 v15, v91, v22
	v_min_u32_e32 v22, v91, v22
	v_max_u32_e32 v91, v89, v28
	v_min_u32_e32 v28, v89, v28
	v_max_u32_e32 v89, v80, v24
	v_min_u32_e32 v24, v80, v24
	v_max_u32_e32 v114, v81, v84
	v_min_u32_e32 v81, v81, v84
	v_max_u32_e32 v84, v19, v87
	v_min_u32_e32 v19, v19, v87
	v_max_u32_e32 v87, v92, v21
	v_min_u32_e32 v21, v92, v21
	v_max_u32_e32 v92, v23, v95
	v_min_u32_e32 v23, v23, v95
	v_max_u32_e32 v95, v97, v25
	v_min_u32_e32 v25, v97, v25
	v_max_u32_e32 v97, v29, v27
	v_min_u32_e32 v27, v29, v27
	v_max_u32_e32 v29, v20, v71
	v_min_u32_e32 v20, v20, v71
	v_max_u32_e32 v71, v17, v73
	v_min_u32_e32 v17, v17, v73
	v_max_u32_e32 v90, v94, v12
	v_min_u32_e32 v12, v94, v12
	v_max_u32_e32 v94, v31, v75
	v_min_u32_e32 v31, v31, v75
	v_max_u32_e32 v75, v78, v30
	v_min_u32_e32 v30, v78, v30
	v_max_u32_e32 v78, v72, v26
	v_min_u32_e32 v26, v72, v26
; __device__ __forceinline__ void phase_route(CArgs& A, int l, unsigned char* lds, int tid) {
;     ...
;             sort16_desc(L3); sort16_desc(g1); sort16_desc(g2); merge16_desc(L3, g1); merge16_desc(L3, g2);
	v_max_u32_e32 v72, v82, v88
	v_min_u32_e32 v82, v82, v88
	v_max_u32_e32 v88, v79, v77
	v_min_u32_e32 v77, v79, v77
	v_max_u32_e32 v79, v85, v70
	v_min_u32_e32 v70, v85, v70
	v_max_u32_e32 v85, v74, v93
	v_min_u32_e32 v74, v74, v93
	v_max_u32_e32 v80, v98, v14
	v_min_u32_e32 v14, v98, v14
	v_max_u32_e32 v98, v18, v16
	v_min_u32_e32 v16, v18, v16
	v_max_u32_e32 v18, v99, v22
	v_min_u32_e32 v22, v99, v22
	v_max_u32_e32 v99, v76, v15
	v_min_u32_e32 v15, v76, v15
	v_max_u32_e32 v76, v86, v28
	v_min_u32_e32 v28, v86, v28
	v_max_u32_e32 v86, v83, v91
	v_min_u32_e32 v83, v83, v91
	v_max_u32_e32 v91, v106, v24
	v_min_u32_e32 v24, v106, v24
	v_max_u32_e32 v106, v13, v89
	v_min_u32_e32 v13, v13, v89
	v_max_u32_e32 v73, v114, v19
	v_min_u32_e32 v19, v114, v19
	v_max_u32_e32 v114, v81, v84
	v_min_u32_e32 v81, v81, v84
	v_max_u32_e32 v84, v23, v87
	v_min_u32_e32 v23, v23, v87
	v_max_u32_e32 v87, v92, v21
	v_min_u32_e32 v21, v92, v21
	v_max_u32_e32 v92, v95, v27
	v_min_u32_e32 v27, v95, v27
	v_max_u32_e32 v95, v25, v97
	v_min_u32_e32 v25, v25, v97
	v_max_u32_e32 v97, v17, v29
	v_min_u32_e32 v17, v17, v29
	v_max_u32_e32 v29, v71, v20
	v_min_u32_e32 v20, v71, v20
	v_max_u32_e32 v93, v90, v72
	v_min_u32_e32 v72, v90, v72
	v_max_u32_e32 v90, v94, v88
	v_min_u32_e32 v88, v94, v88
	v_max_u32_e32 v94, v75, v79
	v_min_u32_e32 v75, v75, v79
	v_max_u32_e32 v79, v78, v85
	v_min_u32_e32 v78, v78, v85
	v_max_u32_e32 v85, v12, v82
	v_min_u32_e32 v12, v12, v82
	v_max_u32_e32 v82, v31, v77
	v_min_u32_e32 v31, v31, v77
	v_max_u32_e32 v77, v30, v70
	v_min_u32_e32 v30, v30, v70
	v_max_u32_e32 v70, v26, v74
	v_min_u32_e32 v26, v26, v74
	v_max_u32_e32 v89, v80, v76
	v_min_u32_e32 v76, v80, v76
	v_max_u32_e32 v80, v98, v86
	v_min_u32_e32 v86, v98, v86
	v_max_u32_e32 v98, v18, v91
	v_min_u32_e32 v18, v18, v91
	v_max_u32_e32 v91, v99, v106
	v_min_u32_e32 v99, v99, v106
	v_max_u32_e32 v106, v14, v28
	v_min_u32_e32 v14, v14, v28
	v_max_u32_e32 v28, v16, v83
	v_min_u32_e32 v16, v16, v83
	v_max_u32_e32 v83, v22, v24
	v_min_u32_e32 v22, v22, v24
	v_max_u32_e32 v24, v15, v13
	v_min_u32_e32 v13, v15, v13
	v_max_u32_e32 v71, v73, v114
	v_min_u32_e32 v73, v73, v114
	v_max_u32_e32 v114, v19, v81
	v_min_u32_e32 v19, v19, v81
	v_max_u32_e32 v81, v21, v23
	v_min_u32_e32 v21, v21, v23
	v_max_u32_e32 v23, v87, v84
	v_min_u32_e32 v84, v87, v84
	v_max_u32_e32 v87, v92, v95
	v_min_u32_e32 v92, v92, v95
	v_max_u32_e32 v95, v27, v25
	v_min_u32_e32 v25, v27, v25
	v_max_u32_e32 v27, v20, v17
	v_min_u32_e32 v17, v20, v17
	v_max_u32_e32 v20, v29, v97
	v_min_u32_e32 v29, v29, v97
	v_max_u32_e32 v74, v93, v94
	v_min_u32_e32 v93, v93, v94
	v_max_u32_e32 v94, v90, v79
	v_min_u32_e32 v79, v90, v79
	v_max_u32_e32 v90, v72, v75
	v_min_u32_e32 v72, v72, v75
	v_max_u32_e32 v75, v88, v78
	v_min_u32_e32 v78, v88, v78
	v_max_u32_e32 v88, v85, v77
	v_min_u32_e32 v77, v85, v77
	v_max_u32_e32 v85, v82, v70
	v_min_u32_e32 v70, v82, v70
	v_max_u32_e32 v82, v12, v30
	v_min_u32_e32 v12, v12, v30
	v_max_u32_e32 v30, v31, v26
	v_min_u32_e32 v26, v31, v26
	v_max_u32_e32 v15, v89, v98
	v_min_u32_e32 v89, v89, v98
	v_max_u32_e32 v98, v80, v91
	v_min_u32_e32 v80, v80, v91
	v_max_u32_e32 v91, v76, v18
	v_min_u32_e32 v18, v76, v18
	v_max_u32_e32 v76, v86, v99
	v_min_u32_e32 v86, v86, v99
	v_max_u32_e32 v99, v106, v83
	v_min_u32_e32 v83, v106, v83
	v_max_u32_e32 v106, v28, v24
	v_min_u32_e32 v24, v28, v24
	v_max_u32_e32 v28, v14, v22
	v_min_u32_e32 v14, v14, v22
	v_max_u32_e32 v22, v16, v13
	v_min_u32_e32 v13, v16, v13
	v_max_u32_e32 v97, v71, v21
	v_min_u32_e32 v21, v71, v21
	v_max_u32_e32 v71, v73, v81
	v_min_u32_e32 v73, v73, v81
	v_max_u32_e32 v81, v114, v84
	v_min_u32_e32 v84, v114, v84
	v_max_u32_e32 v114, v19, v23
	v_min_u32_e32 v19, v19, v23
	v_max_u32_e32 v23, v17, v87
	v_min_u32_e32 v17, v17, v87
	v_max_u32_e32 v87, v27, v92
	v_min_u32_e32 v27, v27, v92
	v_max_u32_e32 v92, v29, v95
	v_min_u32_e32 v29, v29, v95
	v_max_u32_e32 v95, v20, v25
	v_min_u32_e32 v20, v20, v25
	v_min_u32_e32 v31, v74, v94
	v_min_u32_e32 v96, v93, v79
	v_min_u32_e32 v100, v90, v75
	v_min_u32_e32 v101, v72, v78
	v_min_u32_e32 v102, v88, v85
	v_min_u32_e32 v103, v77, v70
	v_min_u32_e32 v104, v82, v30
	v_min_u32_e32 v105, v12, v26
	v_min_u32_e32 v16, v15, v98
	v_min_u32_e32 v107, v89, v80
	v_min_u32_e32 v108, v91, v76
	v_min_u32_e32 v109, v18, v86
	v_min_u32_e32 v110, v99, v106
	v_min_u32_e32 v111, v83, v24
	v_min_u32_e32 v112, v28, v22
	v_min_u32_e32 v113, v14, v13
	v_max_u32_e32 v25, v97, v81
	v_min_u32_e32 v81, v97, v81
	v_max_u32_e32 v97, v71, v114
	v_min_u32_e32 v71, v71, v114
	v_max_u32_e32 v114, v21, v84
	v_min_u32_e32 v21, v21, v84
	v_max_u32_e32 v84, v73, v19
	v_min_u32_e32 v19, v73, v19
	v_max_u32_e32 v73, v29, v17
	v_min_u32_e32 v17, v29, v17
	v_max_u32_e32 v29, v20, v27
	v_min_u32_e32 v20, v20, v27
	v_max_u32_e32 v27, v92, v23
	v_min_u32_e32 v23, v92, v23
	v_max_u32_e32 v92, v95, v87
	v_min_u32_e32 v87, v95, v87
	v_max_u32_e32 v95, v25, v97
	v_min_u32_e32 v25, v25, v97
	v_max_u32_e32 v97, v81, v71
	v_min_u32_e32 v71, v81, v71
	v_max_u32_e32 v81, v114, v84
	v_min_u32_e32 v84, v114, v84
	v_max_u32_e32 v114, v21, v19
	v_min_u32_e32 v19, v21, v19
	v_max_u32_e32 v21, v20, v17
	v_min_u32_e32 v17, v20, v17
	v_max_u32_e32 v20, v29, v73
	v_min_u32_e32 v29, v29, v73
	v_max_u32_e32 v73, v87, v23
	v_min_u32_e32 v23, v87, v23
	v_max_u32_e32 v87, v92, v27
	v_min_u32_e32 v27, v92, v27
	v_max3_u32 v74, v74, v94, v113
	v_max3_u32 v13, v31, v14, v13
	v_max3_u32 v14, v93, v79, v112
	v_max3_u32 v22, v96, v28, v22
	v_max3_u32 v28, v90, v75, v111
	v_max3_u32 v24, v100, v83, v24
	v_max3_u32 v31, v72, v78, v110
	v_max3_u32 v72, v101, v99, v106
; __device__ __forceinline__ unsigned ordf(float f) { unsigned u = __float_as_uint(f); return u ^ ((unsigned)((int)u >> 31) | 0x80000000u); }
; #define INSERT16(L, key) do { unsigned _k = (key); _Pragma("unroll") for (int _j = 0; _j < 16; ++_j) { const unsigned _hi = max(L[_j], _k); _k = min(L[_j], _k); L[_j] = _hi; } } while (0)
; __device__ __forceinline__ void phase_route(CArgs& A, int l, unsigned char* lds, int tid) {
;     ...
;             sort16_desc(L3); sort16_desc(g1); sort16_desc(g2); merge16_desc(L3, g1); merge16_desc(L3, g2);
;             INSERT16(L3, (ordf(v1[CT.i[48]] + v2[CT.j[48]]) & ~0xFFu) | (unsigned)(CT.i[48] * 16 + CT.j[48]));
	v_max3_u32 v75, v88, v85, v109
	v_max3_u32 v18, v102, v18, v86
	v_max3_u32 v70, v77, v70, v108
	v_max3_u32 v76, v103, v91, v76
	v_max3_u32 v30, v82, v30, v107
	v_max3_u32 v77, v104, v89, v80
	v_max3_u32 v12, v12, v26, v16
	v_max3_u32 v15, v105, v15, v98
	v_max_u32_e32 v92, v95, v17
	v_min_u32_e32 v17, v95, v17
	v_max_u32_e32 v95, v25, v21
	v_min_u32_e32 v21, v25, v21
	v_max_u32_e32 v25, v97, v29
	v_min_u32_e32 v29, v97, v29
	v_max_u32_e32 v97, v71, v20
	v_min_u32_e32 v20, v71, v20
	v_max_u32_e32 v71, v81, v23
	v_min_u32_e32 v23, v81, v23
	v_max_u32_e32 v81, v84, v73
	v_min_u32_e32 v73, v84, v73
	v_max_u32_e32 v84, v114, v27
	v_min_u32_e32 v27, v114, v27
	v_max_u32_e32 v114, v19, v87
	v_min_u32_e32 v19, v19, v87
	v_max_u32_e32 v16, v74, v75
	v_min_u32_e32 v26, v74, v75
	v_max_u32_e32 v74, v13, v18
	v_min_u32_e32 v13, v13, v18
	v_max_u32_e32 v18, v14, v70
	v_min_u32_e32 v14, v14, v70
	v_max_u32_e32 v70, v22, v76
	v_min_u32_e32 v22, v22, v76
	v_max_u32_e32 v75, v28, v30
	v_min_u32_e32 v28, v28, v30
	v_max_u32_e32 v30, v24, v77
	v_min_u32_e32 v24, v24, v77
	v_max_u32_e32 v76, v31, v12
	v_min_u32_e32 v12, v31, v12
	v_max_u32_e32 v31, v72, v15
	v_min_u32_e32 v15, v72, v15
	v_max_u32_e32 v87, v92, v71
	v_min_u32_e32 v71, v92, v71
	v_max_u32_e32 v92, v95, v81
	v_min_u32_e32 v81, v95, v81
	v_max_u32_e32 v95, v25, v84
	v_min_u32_e32 v25, v25, v84
	v_max_u32_e32 v84, v97, v114
	v_min_u32_e32 v97, v97, v114
	v_max_u32_e32 v114, v17, v23
	v_min_u32_e32 v17, v17, v23
	v_max_u32_e32 v23, v21, v73
	v_min_u32_e32 v21, v21, v73
	v_max_u32_e32 v73, v29, v27
	v_min_u32_e32 v27, v29, v27
	v_max_u32_e32 v29, v20, v19
	v_min_u32_e32 v19, v20, v19
	v_max_u32_e32 v72, v16, v75
	v_min_u32_e32 v16, v16, v75
	v_max_u32_e32 v75, v74, v30
	v_min_u32_e32 v30, v74, v30
	v_max_u32_e32 v74, v18, v76
	v_min_u32_e32 v18, v18, v76
	v_max_u32_e32 v76, v70, v31
	v_min_u32_e32 v31, v70, v31
	v_max_u32_e32 v70, v26, v28
	v_min_u32_e32 v26, v26, v28
	v_max_u32_e32 v28, v13, v24
	v_min_u32_e32 v13, v13, v24
	v_max_u32_e32 v24, v14, v12
	v_min_u32_e32 v12, v14, v12
	v_max_u32_e32 v14, v22, v15
	v_min_u32_e32 v15, v22, v15
	v_max_u32_e32 v20, v87, v95
	v_min_u32_e32 v87, v87, v95
	v_max_u32_e32 v95, v92, v84
	v_min_u32_e32 v84, v92, v84
	v_max_u32_e32 v92, v71, v25
	v_min_u32_e32 v25, v71, v25
	v_max_u32_e32 v71, v81, v97
	v_min_u32_e32 v81, v81, v97
	v_max_u32_e32 v97, v114, v73
	v_min_u32_e32 v73, v114, v73
	v_max_u32_e32 v114, v23, v29
	v_min_u32_e32 v23, v23, v29
	v_max_u32_e32 v29, v17, v27
	v_min_u32_e32 v17, v17, v27
	v_max_u32_e32 v27, v21, v19
	v_min_u32_e32 v19, v21, v19
	v_max_u32_e32 v22, v72, v74
	v_min_u32_e32 v72, v72, v74
	v_max_u32_e32 v74, v75, v76
	v_min_u32_e32 v75, v75, v76
	v_max_u32_e32 v76, v16, v18
	v_min_u32_e32 v16, v16, v18
	v_max_u32_e32 v18, v30, v31
	v_min_u32_e32 v30, v30, v31
	v_max_u32_e32 v31, v70, v24
	v_min_u32_e32 v24, v70, v24
	v_max_u32_e32 v70, v28, v14
	v_min_u32_e32 v14, v28, v14
	v_max_u32_e32 v28, v26, v12
	v_min_u32_e32 v12, v26, v12
	v_max_u32_e32 v26, v13, v15
	v_min_u32_e32 v13, v13, v15
	v_min_u32_e32 v21, v20, v95
	v_min_u32_e32 v115, v87, v84
	v_min_u32_e32 v116, v92, v71
	v_min_u32_e32 v117, v25, v81
	v_min_u32_e32 v118, v97, v114
	v_min_u32_e32 v119, v73, v23
	v_min_u32_e32 v120, v29, v27
	v_min_u32_e32 v121, v17, v19
	v_min_u32_e32 v15, v22, v74
	v_min_u32_e32 v77, v72, v75
	v_min_u32_e32 v78, v76, v18
	v_min_u32_e32 v79, v16, v30
	v_min_u32_e32 v80, v31, v70
	v_min_u32_e32 v82, v24, v14
	v_min_u32_e32 v83, v28, v26
	v_min_u32_e32 v85, v12, v13
	v_max3_u32 v22, v22, v74, v121
	v_max3_u32 v15, v15, v17, v19
	v_max3_u32 v17, v72, v75, v120
	v_max3_u32 v19, v77, v29, v27
	v_max3_u32 v18, v76, v18, v119
	v_max3_u32 v23, v78, v73, v23
	v_max3_u32 v16, v16, v30, v118
	v_max3_u32 v27, v79, v97, v114
	v_max3_u32 v29, v31, v70, v117
	v_max3_u32 v25, v80, v25, v81
	v_max3_u32 v14, v24, v14, v116
	v_max3_u32 v24, v82, v92, v71
	v_max3_u32 v26, v28, v26, v115
	v_max3_u32 v28, v83, v87, v84
	v_max3_u32 v12, v12, v13, v21
	v_max3_u32 v13, v85, v20, v95
	v_max_u32_e32 v20, v22, v29
	v_min_u32_e32 v21, v22, v29
	v_max_u32_e32 v22, v15, v25
	v_min_u32_e32 v15, v15, v25
	v_max_u32_e32 v25, v17, v14
	v_min_u32_e32 v14, v17, v14
	v_max_u32_e32 v17, v19, v24
	v_min_u32_e32 v19, v19, v24
	v_max_u32_e32 v24, v18, v26
	v_min_u32_e32 v18, v18, v26
	v_max_u32_e32 v26, v23, v28
	v_min_u32_e32 v23, v23, v28
	v_max_u32_e32 v28, v16, v12
	v_min_u32_e32 v12, v16, v12
	v_max_u32_e32 v16, v27, v13
	v_min_u32_e32 v13, v27, v13
	v_max_u32_e32 v27, v20, v24
	v_min_u32_e32 v20, v20, v24
	v_max_u32_e32 v24, v22, v26
	v_min_u32_e32 v22, v22, v26
	v_max_u32_e32 v26, v25, v28
	v_min_u32_e32 v25, v25, v28
	v_max_u32_e32 v28, v17, v16
	v_min_u32_e32 v16, v17, v16
	v_max_u32_e32 v17, v21, v18
	v_min_u32_e32 v18, v21, v18
	v_max_u32_e32 v21, v15, v23
	v_min_u32_e32 v15, v15, v23
	v_max_u32_e32 v23, v14, v12
	v_min_u32_e32 v12, v14, v12
	v_max_u32_e32 v14, v19, v13
	v_min_u32_e32 v13, v19, v13
	v_max_u32_e32 v19, v27, v26
	v_min_u32_e32 v26, v27, v26
	v_max_u32_e32 v27, v24, v28
	v_min_u32_e32 v24, v24, v28
	v_max_u32_e32 v28, v20, v25
	v_min_u32_e32 v20, v20, v25
	v_max_u32_e32 v25, v22, v16
	v_min_u32_e32 v16, v22, v16
	v_max_u32_e32 v22, v17, v23
	v_min_u32_e32 v17, v17, v23
	v_max_u32_e32 v23, v21, v14
	v_min_u32_e32 v14, v21, v14
	v_max_u32_e32 v21, v18, v12
	v_min_u32_e32 v12, v18, v12
	v_max_u32_e32 v18, v15, v13
	v_min_u32_e32 v13, v15, v13
	v_add_f32_e32 v10, v3, v10
	v_max_u32_e32 v80, v12, v13
	v_min_u32_e32 v12, v12, v13
	v_ashrrev_i32_e32 v13, 31, v10
	v_or_b32_e32 v13, 0x80000000, v13
	v_bitop3_b32 v10, v13, s82, v10 bitop3:0x48
	v_max_u32_e32 v15, v19, v27
; __device__ __forceinline__ unsigned ordf(float f) { unsigned u = __float_as_uint(f); return u ^ ((unsigned)((int)u >> 31) | 0x80000000u); }
; __device__ __forceinline__ float unordf(unsigned v) { return __uint_as_float(v ^ ((~(unsigned)((int)v >> 31)) | 0x80000000u)); }
; #define INSERT16(L, key) do { unsigned _k = (key); _Pragma("unroll") for (int _j = 0; _j < 16; ++_j) { const unsigned _hi = max(L[_j], _k); _k = min(L[_j], _k); L[_j] = _hi; } } while (0)
; __device__ __forceinline__ void phase_route(CArgs& A, int l, unsigned char* lds, int tid) {
;     ...
;             INSERT16(L3, (ordf(v1[CT.i[48]] + v2[CT.j[48]]) & ~0xFFu) | (unsigned)(CT.i[48] * 16 + CT.j[48]));
;             INSERT16(L3, (ordf(v1[CT.i[49]] + v2[CT.j[49]]) & ~0xFFu) | (unsigned)(CT.i[49] * 16 + CT.j[49]));
;             static_assert(CT.i[49] >= 0 && CT.i[50] < 0, "50 candidates");
;         }
;         float e[16], sum = 0.f; const float mx = unordf(L3[0] & ~0xFFu);
; #pragma unroll
;         for (int k = 0; k < 16; ++k) { e[k] = expf(unordf(L3[k] & ~0xFFu) - mx); sum += e[k]; }
	v_or_b32_e32 v10, 0xe0, v10
	v_min_u32_e32 v29, v19, v27
	v_max_u32_e32 v13, v15, v10
	v_min_u32_e32 v15, v15, v10
	v_max_u32_e32 v30, v26, v24
	v_min_u32_e32 v15, v29, v15
	v_min_u32_e32 v31, v26, v24
	v_med3_u32 v10, v19, v27, v10
	v_min_u32_e32 v27, v30, v15
	v_max_u32_e32 v70, v28, v25
	v_max_u32_e32 v19, v30, v15
	v_med3_u32 v15, v26, v24, v15
	v_min_u32_e32 v24, v31, v27
	v_min_u32_e32 v71, v28, v25
	v_min_u32_e32 v27, v70, v24
	v_max_u32_e32 v72, v20, v16
	v_max_u32_e32 v26, v70, v24
	v_med3_u32 v24, v28, v25, v24
	v_min_u32_e32 v25, v71, v27
	v_pk_add_f32 v[2:3], v[2:3], v[2:3] op_sel:[1,0] op_sel_hi:[0,1]
	v_min_u32_e32 v73, v20, v16
	v_min_u32_e32 v28, v72, v25
	v_ashrrev_i32_e32 v3, 31, v2
	v_max_u32_e32 v74, v22, v23
	v_med3_u32 v16, v20, v16, v25
	v_min_u32_e32 v20, v73, v28
	v_or_b32_e32 v3, 0x80000000, v3
	v_min_u32_e32 v75, v22, v23
	v_min_u32_e32 v28, v74, v20
	v_bitop3_b32 v2, v3, s82, v2 bitop3:0x48
	v_max_u32_e32 v76, v17, v14
	v_max_u32_e32 v27, v72, v25
	v_max_u32_e32 v25, v74, v20
	v_med3_u32 v20, v22, v23, v20
	v_min_u32_e32 v22, v75, v28
	v_or_b32_e32 v2, 0xf0, v2
	v_min_u32_e32 v77, v17, v14
	v_min_u32_e32 v28, v76, v22
	v_max_u32_e32 v73, v13, v2
	v_min_u32_e32 v2, v13, v2
	v_max_u32_e32 v78, v21, v18
	v_med3_u32 v14, v17, v14, v22
	v_min_u32_e32 v17, v77, v28
	v_max_u32_e32 v74, v10, v2
	v_min_u32_e32 v2, v10, v2
	v_min_u32_e32 v79, v21, v18
	v_max_u32_e32 v23, v76, v22
	v_min_u32_e32 v28, v78, v17
	v_max_u32_e32 v76, v19, v2
	v_min_u32_e32 v2, v19, v2
	v_max_u32_e32 v22, v78, v17
	v_med3_u32 v17, v21, v18, v17
	v_min_u32_e32 v18, v79, v28
	v_max_u32_e32 v78, v15, v2
	v_min_u32_e32 v2, v15, v2
	v_max_u32_e32 v21, v80, v18
	v_min_u32_e32 v18, v80, v18
	v_max_u32_e32 v80, v26, v2
	v_min_u32_e32 v2, v26, v2
	v_max_u32_e32 v82, v24, v2
	v_min_u32_e32 v2, v24, v2
	v_max_u32_e32 v83, v27, v2
	v_min_u32_e32 v2, v27, v2
	v_max_u32_e32 v84, v16, v2
	v_min_u32_e32 v2, v16, v2
	v_max_u32_e32 v75, v25, v2
	v_min_u32_e32 v2, v25, v2
	v_cmp_lt_i32_e32 vcc, -1, v73
	v_max_u32_e32 v77, v20, v2
	v_min_u32_e32 v2, v20, v2
	v_cndmask_b32_e64 v13, v182, -1, vcc
	v_max_u32_e32 v79, v23, v2
	v_min_u32_e32 v2, v23, v2
	v_bitop3_b32 v13, v13, v73, s82 bitop3:0x78
	v_max_u32_e32 v81, v14, v2
	v_min_u32_e32 v3, v14, v2
	v_sub_f32_e32 v14, v13, v13
	v_min_u32_e32 v10, v22, v3
	v_mul_f32_e32 v15, 0x3fb8aa3b, v14
	v_max_u32_e32 v2, v22, v3
	v_max_u32_e32 v3, v17, v10
	v_min_u32_e32 v10, v17, v10
	v_fma_f32 v16, v14, s83, -v15
	v_rndne_f32_e32 v17, v15
	v_fmac_f32_e32 v16, 0x32a5705f, v14
	v_sub_f32_e32 v15, v15, v17
	v_add_f32_e32 v15, v15, v16
	v_exp_f32_e32 v15, v15
	v_cvt_i32_f32_e32 v16, v17
	v_max_u32_e32 v85, v21, v10
	v_min_u32_e32 v10, v21, v10
	v_cmp_lt_i32_e32 vcc, -1, v74
	v_max3_u32 v86, v12, v18, v10
	v_ldexp_f32 v10, v15, v16
	v_cndmask_b32_e64 v12, v182, -1, vcc
	v_bitop3_b32 v12, v12, v74, s82 bitop3:0x78
	v_sub_f32_e32 v12, v12, v13
	v_mul_f32_e32 v15, 0x3fb8aa3b, v12
	v_fma_f32 v16, v12, s83, -v15
	v_rndne_f32_e32 v17, v15
	v_fmac_f32_e32 v16, 0x32a5705f, v12
	v_sub_f32_e32 v15, v15, v17
	v_add_f32_e32 v15, v15, v16
	v_exp_f32_e32 v15, v15
	v_cvt_i32_f32_e32 v17, v17
	v_cmp_ngt_f32_e32 vcc, s76, v14
	v_and_b32_e32 v6, 0x7f, v6
	v_and_b32_e32 v45, 0x7f, v45
	v_cndmask_b32_e32 v10, 0, v10, vcc
	v_cmp_nlt_f32_e32 vcc, s77, v14
	v_and_b32_e32 v46, 0x7f, v46
	v_and_b32_e32 v48, 0x7f, v48
	v_cndmask_b32_e32 v16, v181, v10, vcc
	v_ldexp_f32 v10, v15, v17
	v_cmp_ngt_f32_e32 vcc, s76, v12
	v_and_b32_e32 v49, 0x7f, v49
	v_and_b32_e32 v50, 0x7f, v50
	v_cndmask_b32_e32 v10, 0, v10, vcc
	v_cmp_lt_i32_e32 vcc, -1, v76
	v_and_b32_e32 v51, 0x7f, v51
	v_and_b32_e32 v52, 0x7f, v52
	v_cndmask_b32_e64 v14, v182, -1, vcc
	v_bitop3_b32 v14, v14, v76, s82 bitop3:0x78
	v_sub_f32_e32 v14, v14, v13
	v_mul_f32_e32 v15, 0x3fb8aa3b, v14
	v_fma_f32 v17, v14, s83, -v15
	v_rndne_f32_e32 v18, v15
	v_fmac_f32_e32 v17, 0x32a5705f, v14
	v_sub_f32_e32 v15, v15, v18
	v_add_f32_e32 v15, v15, v17
	v_exp_f32_e32 v15, v15
	v_cvt_i32_f32_e32 v18, v18
	v_cmp_nlt_f32_e32 vcc, s77, v12
	v_and_b32_e32 v53, 0x7f, v53
	v_and_b32_e32 v67, 0x7f, v67
	v_cndmask_b32_e32 v17, v181, v10, vcc
	v_ldexp_f32 v12, v15, v18
	v_cmp_ngt_f32_e32 vcc, s76, v14
	v_add_f32_e32 v10, v16, v17
	v_and_b32_e32 v69, 0x7f, v69
	v_cndmask_b32_e32 v12, 0, v12, vcc
	v_cmp_lt_i32_e32 vcc, -1, v78
	v_and_b32_e32 v71, 0x7f, v9
	v_and_b32_e32 v72, 0x7f, v4
	v_cndmask_b32_e64 v15, v182, -1, vcc
	v_bitop3_b32 v15, v15, v78, s82 bitop3:0x78
	v_sub_f32_e32 v15, v15, v13
	v_mul_f32_e32 v18, 0x3fb8aa3b, v15
	v_fma_f32 v19, v15, s83, -v18
	v_rndne_f32_e32 v20, v18
	v_fmac_f32_e32 v19, 0x32a5705f, v15
	v_sub_f32_e32 v18, v18, v20
	v_add_f32_e32 v18, v18, v19
	v_exp_f32_e32 v19, v18
	v_cvt_i32_f32_e32 v20, v20
	v_cmp_nlt_f32_e32 vcc, s77, v14
	s_nop 1
	v_cndmask_b32_e32 v18, v181, v12, vcc
	v_ldexp_f32 v12, v19, v20
	v_cmp_ngt_f32_e32 vcc, s76, v15
	v_add_f32_e32 v10, v10, v18
	s_nop 0
	v_cndmask_b32_e32 v12, 0, v12, vcc
	v_cmp_lt_i32_e32 vcc, -1, v80
	s_nop 1
	v_cndmask_b32_e64 v14, v182, -1, vcc
	v_bitop3_b32 v14, v14, v80, s82 bitop3:0x78
	v_sub_f32_e32 v14, v14, v13
	v_mul_f32_e32 v19, 0x3fb8aa3b, v14
	v_fma_f32 v20, v14, s83, -v19
	v_rndne_f32_e32 v21, v19
	v_fmac_f32_e32 v20, 0x32a5705f, v14
	v_sub_f32_e32 v19, v19, v21
	v_add_f32_e32 v19, v19, v20
	v_exp_f32_e32 v20, v19
	v_cvt_i32_f32_e32 v21, v21
	v_cmp_nlt_f32_e32 vcc, s77, v15
	s_nop 1
	v_cndmask_b32_e32 v19, v181, v12, vcc
	v_ldexp_f32 v12, v20, v21
	v_cmp_ngt_f32_e32 vcc, s76, v14
	v_add_f32_e32 v10, v10, v19
	s_nop 0
	v_cndmask_b32_e32 v12, 0, v12, vcc
	v_cmp_lt_i32_e32 vcc, -1, v82
	s_nop 1
	v_cndmask_b32_e64 v15, v182, -1, vcc
; __device__ __forceinline__ float unordf(unsigned v) { return __uint_as_float(v ^ ((~(unsigned)((int)v >> 31)) | 0x80000000u)); }
; __device__ __forceinline__ void phase_route(CArgs& A, int l, unsigned char* lds, int tid) {
;     ...
;         for (int k = 0; k < 16; ++k) { e[k] = expf(unordf(L3[k] & ~0xFFu) - mx); sum += e[k]; }
	v_bitop3_b32 v15, v15, v82, s82 bitop3:0x78
	v_sub_f32_e32 v15, v15, v13
	v_mul_f32_e32 v20, 0x3fb8aa3b, v15
	v_fma_f32 v21, v15, s83, -v20
	v_rndne_f32_e32 v22, v20
	v_fmac_f32_e32 v21, 0x32a5705f, v15
	v_sub_f32_e32 v20, v20, v22
	v_add_f32_e32 v20, v20, v21
	v_exp_f32_e32 v21, v20
	v_cvt_i32_f32_e32 v22, v22
	v_cmp_nlt_f32_e32 vcc, s77, v14
	s_nop 1
	v_cndmask_b32_e32 v20, v181, v12, vcc
	v_ldexp_f32 v12, v21, v22
	v_cmp_ngt_f32_e32 vcc, s76, v15
	v_add_f32_e32 v10, v10, v20
	s_nop 0
	v_cndmask_b32_e32 v12, 0, v12, vcc
	v_cmp_lt_i32_e32 vcc, -1, v83
	s_nop 1
	v_cndmask_b32_e64 v14, v182, -1, vcc
	v_bitop3_b32 v14, v14, v83, s82 bitop3:0x78
	v_sub_f32_e32 v14, v14, v13
	v_mul_f32_e32 v21, 0x3fb8aa3b, v14
	v_fma_f32 v22, v14, s83, -v21
	v_rndne_f32_e32 v23, v21
	v_fmac_f32_e32 v22, 0x32a5705f, v14
	v_sub_f32_e32 v21, v21, v23
	v_add_f32_e32 v21, v21, v22
	v_exp_f32_e32 v22, v21
	v_cvt_i32_f32_e32 v23, v23
	v_cmp_nlt_f32_e32 vcc, s77, v15
	s_nop 1
	v_cndmask_b32_e32 v21, v181, v12, vcc
	v_ldexp_f32 v12, v22, v23
	v_cmp_ngt_f32_e32 vcc, s76, v14
	v_add_f32_e32 v10, v10, v21
	s_nop 0
	v_cndmask_b32_e32 v12, 0, v12, vcc
	v_cmp_lt_i32_e32 vcc, -1, v84
	s_nop 1
	v_cndmask_b32_e64 v15, v182, -1, vcc
	v_bitop3_b32 v15, v15, v84, s82 bitop3:0x78
	v_sub_f32_e32 v15, v15, v13
	v_mul_f32_e32 v22, 0x3fb8aa3b, v15
	v_fma_f32 v23, v15, s83, -v22
	v_rndne_f32_e32 v24, v22
	v_fmac_f32_e32 v23, 0x32a5705f, v15
	v_sub_f32_e32 v22, v22, v24
	v_add_f32_e32 v22, v22, v23
	v_exp_f32_e32 v23, v22
	v_cvt_i32_f32_e32 v24, v24
	v_cmp_nlt_f32_e32 vcc, s77, v14
	s_nop 1
	v_cndmask_b32_e32 v22, v181, v12, vcc
	v_ldexp_f32 v12, v23, v24
	v_cmp_ngt_f32_e32 vcc, s76, v15
	v_add_f32_e32 v10, v10, v22
	s_nop 0
	v_cndmask_b32_e32 v12, 0, v12, vcc
	v_cmp_lt_i32_e32 vcc, -1, v75
	s_nop 1
	v_cndmask_b32_e64 v14, v182, -1, vcc
	v_bitop3_b32 v14, v14, v75, s82 bitop3:0x78
	v_sub_f32_e32 v14, v14, v13
	v_mul_f32_e32 v23, 0x3fb8aa3b, v14
	v_fma_f32 v24, v14, s83, -v23
	v_rndne_f32_e32 v25, v23
	v_fmac_f32_e32 v24, 0x32a5705f, v14
	v_sub_f32_e32 v23, v23, v25
	v_add_f32_e32 v23, v23, v24
	v_exp_f32_e32 v24, v23
	v_cvt_i32_f32_e32 v25, v25
	v_cmp_nlt_f32_e32 vcc, s77, v15
	s_nop 1
	v_cndmask_b32_e32 v23, v181, v12, vcc
	v_ldexp_f32 v12, v24, v25
	v_cmp_ngt_f32_e32 vcc, s76, v14
	v_add_f32_e32 v10, v10, v23
	s_nop 0
	v_cndmask_b32_e32 v12, 0, v12, vcc
	v_cmp_lt_i32_e32 vcc, -1, v77
	s_nop 1
	v_cndmask_b32_e64 v15, v182, -1, vcc
	v_bitop3_b32 v15, v15, v77, s82 bitop3:0x78
	v_sub_f32_e32 v15, v15, v13
	v_mul_f32_e32 v24, 0x3fb8aa3b, v15
	v_fma_f32 v25, v15, s83, -v24
	v_rndne_f32_e32 v26, v24
	v_fmac_f32_e32 v25, 0x32a5705f, v15
	v_sub_f32_e32 v24, v24, v26
	v_add_f32_e32 v24, v24, v25
	v_exp_f32_e32 v25, v24
	v_cvt_i32_f32_e32 v26, v26
	v_cmp_nlt_f32_e32 vcc, s77, v14
	s_nop 1
	v_cndmask_b32_e32 v24, v181, v12, vcc
	v_ldexp_f32 v12, v25, v26
	v_cmp_ngt_f32_e32 vcc, s76, v15
	v_add_f32_e32 v10, v10, v24
	s_nop 0
	v_cndmask_b32_e32 v12, 0, v12, vcc
	v_cmp_lt_i32_e32 vcc, -1, v79
	s_nop 1
	v_cndmask_b32_e64 v14, v182, -1, vcc
	v_bitop3_b32 v14, v14, v79, s82 bitop3:0x78
	v_sub_f32_e32 v14, v14, v13
	v_mul_f32_e32 v25, 0x3fb8aa3b, v14
	v_fma_f32 v26, v14, s83, -v25
	v_rndne_f32_e32 v27, v25
	v_fmac_f32_e32 v26, 0x32a5705f, v14
	v_sub_f32_e32 v25, v25, v27
	v_add_f32_e32 v25, v25, v26
	v_exp_f32_e32 v26, v25
	v_cvt_i32_f32_e32 v27, v27
	v_cmp_nlt_f32_e32 vcc, s77, v15
	s_nop 1
	v_cndmask_b32_e32 v25, v181, v12, vcc
	v_ldexp_f32 v12, v26, v27
	v_cmp_ngt_f32_e32 vcc, s76, v14
	v_add_f32_e32 v10, v10, v25
	s_nop 0
	v_cndmask_b32_e32 v12, 0, v12, vcc
	v_cmp_lt_i32_e32 vcc, -1, v81
	s_nop 1
	v_cndmask_b32_e64 v15, v182, -1, vcc
	v_bitop3_b32 v15, v15, v81, s82 bitop3:0x78
	v_sub_f32_e32 v15, v15, v13
	v_mul_f32_e32 v26, 0x3fb8aa3b, v15
	v_fma_f32 v27, v15, s83, -v26
	v_rndne_f32_e32 v28, v26
	v_fmac_f32_e32 v27, 0x32a5705f, v15
	v_sub_f32_e32 v26, v26, v28
	v_add_f32_e32 v26, v26, v27
	v_exp_f32_e32 v27, v26
	v_cvt_i32_f32_e32 v28, v28
	v_cmp_nlt_f32_e32 vcc, s77, v14
	s_nop 1
	v_cndmask_b32_e32 v26, v181, v12, vcc
	v_ldexp_f32 v12, v27, v28
	v_cmp_ngt_f32_e32 vcc, s76, v15
	v_add_f32_e32 v10, v10, v26
	s_nop 0
	v_cndmask_b32_e32 v12, 0, v12, vcc
	v_cmp_lt_i32_e32 vcc, -1, v2
	s_nop 1
	v_cndmask_b32_e64 v14, v182, -1, vcc
	v_bitop3_b32 v14, v14, v2, s82 bitop3:0x78
	v_sub_f32_e32 v14, v14, v13
	v_mul_f32_e32 v27, 0x3fb8aa3b, v14
	v_fma_f32 v28, v14, s83, -v27
	v_rndne_f32_e32 v29, v27
	v_fmac_f32_e32 v28, 0x32a5705f, v14
	v_sub_f32_e32 v27, v27, v29
	v_add_f32_e32 v27, v27, v28
	v_exp_f32_e32 v28, v27
	v_cvt_i32_f32_e32 v29, v29
	v_cmp_nlt_f32_e32 vcc, s77, v15
	s_nop 1
	v_cndmask_b32_e32 v27, v181, v12, vcc
	v_ldexp_f32 v12, v28, v29
	v_cmp_ngt_f32_e32 vcc, s76, v14
	v_add_f32_e32 v10, v10, v27
	s_nop 0
	v_cndmask_b32_e32 v12, 0, v12, vcc
	v_cmp_lt_i32_e32 vcc, -1, v3
	s_nop 1
	v_cndmask_b32_e64 v15, v182, -1, vcc
	v_bitop3_b32 v15, v15, v3, s82 bitop3:0x78
	v_sub_f32_e32 v15, v15, v13
	v_mul_f32_e32 v28, 0x3fb8aa3b, v15
	v_fma_f32 v29, v15, s83, -v28
	v_rndne_f32_e32 v30, v28
	v_fmac_f32_e32 v29, 0x32a5705f, v15
	v_sub_f32_e32 v28, v28, v30
	v_add_f32_e32 v28, v28, v29
	v_exp_f32_e32 v29, v28
	v_cvt_i32_f32_e32 v30, v30
	v_cmp_nlt_f32_e32 vcc, s77, v14
	s_nop 1
	v_cndmask_b32_e32 v28, v181, v12, vcc
	v_ldexp_f32 v12, v29, v30
	v_cmp_ngt_f32_e32 vcc, s76, v15
	v_add_f32_e32 v10, v10, v28
	s_nop 0
	v_cndmask_b32_e32 v12, 0, v12, vcc
	v_cmp_lt_i32_e32 vcc, -1, v85
	s_nop 1
	v_cndmask_b32_e64 v14, v182, -1, vcc
	v_bitop3_b32 v14, v14, v85, s82 bitop3:0x78
	v_sub_f32_e32 v14, v14, v13
	v_mul_f32_e32 v29, 0x3fb8aa3b, v14
	v_fma_f32 v30, v14, s83, -v29
	v_rndne_f32_e32 v31, v29
; __device__ __forceinline__ void phase_route(CArgs& A, int l, unsigned char* lds, int tid) {
;     ...
;         const float inv = 1.f / sum;
;         int ex[16];
; #pragma unroll
;         for (int k = 0; k < 16; ++k) { const unsigned ci = L3[k] & 0xFFu, i = ci >> 4, j = ci & 15u; unsigned e1 = 0u, e2 = 0u;
; #pragma unroll
;             for (int ii = 0; ii < 16; ++ii) { e1 = (i == (unsigned)ii) ? (L1[ii] & 0x7Fu) : e1; e2 = (j == (unsigned)ii) ? (L2[ii] & 0x7Fu) : e2; }
;             ex[k] = (int)(e1 * 128u + e2); e[k] *= inv; }
	v_fmac_f32_e32 v30, 0x32a5705f, v14
	v_sub_f32_e32 v29, v29, v31
	v_add_f32_e32 v29, v29, v30
	v_exp_f32_e32 v30, v29
	v_cvt_i32_f32_e32 v31, v31
	v_cmp_nlt_f32_e32 vcc, s77, v15
	s_nop 1
	v_cndmask_b32_e32 v29, v181, v12, vcc
	v_ldexp_f32 v12, v30, v31
	v_cmp_ngt_f32_e32 vcc, s76, v14
	v_add_f32_e32 v10, v10, v29
	s_nop 0
	v_cndmask_b32_e32 v12, 0, v12, vcc
	v_cmp_lt_i32_e32 vcc, -1, v86
	s_nop 1
	v_cndmask_b32_e64 v15, v182, -1, vcc
	v_bitop3_b32 v15, v15, v86, s82 bitop3:0x78
	v_sub_f32_e32 v13, v15, v13
	v_mul_f32_e32 v15, 0x3fb8aa3b, v13
	v_fma_f32 v30, v13, s83, -v15
	v_rndne_f32_e32 v31, v15
	v_fmac_f32_e32 v30, 0x32a5705f, v13
	v_sub_f32_e32 v15, v15, v31
	v_add_f32_e32 v15, v15, v30
	v_exp_f32_e32 v15, v15
	v_cvt_i32_f32_e32 v31, v31
	v_cmp_nlt_f32_e32 vcc, s77, v14
	s_nop 1
	v_cndmask_b32_e32 v30, v181, v12, vcc
	v_ldexp_f32 v12, v15, v31
	v_cmp_ngt_f32_e32 vcc, s76, v13
	v_add_f32_e32 v10, v10, v30
	s_nop 0
	v_cndmask_b32_e32 v12, 0, v12, vcc
	v_cmp_nlt_f32_e32 vcc, s77, v13
	s_nop 1
	v_cndmask_b32_e32 v31, v181, v12, vcc
	v_add_f32_e32 v10, v10, v31
	v_div_scale_f32 v12, s[0:1], v10, v10, 1.0
	v_rcp_f32_e32 v13, v12
	s_nop 0
	v_fma_f32 v14, -v12, v13, 1.0
	v_fmac_f32_e32 v13, v14, v13
	v_div_scale_f32 v14, vcc, 1.0, v10, 1.0
	v_mul_f32_e32 v15, v14, v13
	v_fma_f32 v70, -v12, v15, v14
	v_fmac_f32_e32 v15, v70, v13
	v_fma_f32 v12, -v12, v15, v14
	v_div_fmas_f32 v12, v12, v13, v15
	v_div_fixup_f32 v10, v12, v10, 1.0
	v_lshlrev_b64 v[12:13], 9, v[60:61]
	v_lshl_add_u64 v[14:15], v[54:55], 0, v[12:13]
	v_lshl_add_u64 v[12:13], v[56:57], 0, v[12:13]
	v_and_b32_e32 v60, 0x7f, v68
	v_and_b32_e32 v61, 0x7f, v8
	v_and_b32_e32 v68, 0x7f, v7
	v_and_b32_e32 v70, 0x7f, v5
	s_and_saveexec_b64 s[0:1], s[40:41]
	s_xor_b64 s[4:5], exec, s[0:1]
	s_cbranch_execz .LBB0_137
	v_and_b32_e32 v4, 15, v86
	v_cmp_eq_u32_e32 vcc, 0, v4
	v_mov_b64_e32 v[22:23], v[30:31]
	v_mov_b64_e32 v[20:21], v[28:29]
	v_cndmask_b32_e32 v5, 0, v45, vcc
	v_cmp_eq_u32_e64 s[98:99], 1, v4
	v_cmp_eq_u32_e32 vcc, 2, v4
	v_cmp_eq_u32_e64 s[100:101], 3, v4
	v_cndmask_b32_e64 v5, v5, v44, s[98:99]
	v_cmp_eq_u32_e64 s[98:99], 4, v4
	v_cndmask_b32_e32 v5, v5, v43, vcc
	v_cmp_eq_u32_e32 vcc, 5, v4
	v_cndmask_b32_e64 v5, v5, v42, s[100:101]
	v_cmp_eq_u32_e64 s[100:101], 6, v4
	v_cndmask_b32_e64 v5, v5, v41, s[98:99]
	v_cmp_eq_u32_e64 s[98:99], 7, v4
	v_cndmask_b32_e32 v5, v5, v40, vcc
	v_cmp_eq_u32_e32 vcc, 8, v4
	v_cndmask_b32_e64 v5, v5, v39, s[100:101]
	v_cmp_eq_u32_e64 s[100:101], 9, v4
	v_cndmask_b32_e64 v5, v5, v38, s[98:99]
	v_cmp_eq_u32_e64 s[98:99], 10, v4
	v_cndmask_b32_e32 v5, v5, v37, vcc
	v_cmp_eq_u32_e32 vcc, 11, v4
	v_cndmask_b32_e64 v5, v5, v36, s[100:101]
	v_cmp_eq_u32_e64 s[100:101], 12, v4
	v_cndmask_b32_e64 v5, v5, v35, s[98:99]
	v_cmp_eq_u32_e64 s[98:99], 13, v4
	v_cndmask_b32_e32 v5, v5, v34, vcc
	v_cmp_eq_u32_e32 vcc, 14, v4
	v_cndmask_b32_e64 v5, v5, v33, s[100:101]
	v_cndmask_b32_e64 v5, v5, v32, s[98:99]
	v_cndmask_b32_e32 v5, v5, v11, vcc
	v_cmp_eq_u32_e32 vcc, 15, v4
	v_bfe_u32 v4, v86, 4, 4
	s_nop 0
	v_cndmask_b32_e32 v5, v5, v6, vcc
	v_cmp_eq_u32_e64 s[100:101], 0, v4
	v_cmp_eq_u32_e64 s[98:99], 1, v4
	v_cmp_eq_u32_e32 vcc, 2, v4
	v_cndmask_b32_e64 v7, 0, v72, s[100:101]
	v_cmp_eq_u32_e64 s[100:101], 3, v4
	v_cndmask_b32_e64 v7, v7, v71, s[98:99]
	v_cmp_eq_u32_e64 s[98:99], 4, v4
	v_cndmask_b32_e32 v7, v7, v70, vcc
	v_cmp_eq_u32_e32 vcc, 5, v4
	v_cndmask_b32_e64 v7, v7, v69, s[100:101]
	v_cmp_eq_u32_e64 s[100:101], 6, v4
	v_cndmask_b32_e64 v7, v7, v68, s[98:99]
	v_cmp_eq_u32_e64 s[98:99], 7, v4
	v_cndmask_b32_e32 v7, v7, v67, vcc
	v_cmp_eq_u32_e32 vcc, 8, v4
	v_cndmask_b32_e64 v7, v7, v61, s[100:101]
	v_cmp_eq_u32_e64 s[100:101], 9, v4
	v_cndmask_b32_e64 v7, v7, v60, s[98:99]
	v_cmp_eq_u32_e64 s[98:99], 10, v4
	v_cndmask_b32_e32 v7, v7, v53, vcc
	v_cmp_eq_u32_e32 vcc, 11, v4
	v_cndmask_b32_e64 v7, v7, v52, s[100:101]
	v_cmp_eq_u32_e64 s[100:101], 12, v4
	v_cndmask_b32_e64 v7, v7, v51, s[98:99]
	v_cmp_eq_u32_e64 s[98:99], 13, v4
	v_cndmask_b32_e32 v7, v7, v50, vcc
	v_cmp_eq_u32_e32 vcc, 14, v4
	v_cndmask_b32_e64 v7, v7, v49, s[100:101]
	v_cndmask_b32_e64 v7, v7, v48, s[98:99]
	v_cndmask_b32_e32 v7, v7, v47, vcc
	v_cmp_eq_u32_e32 vcc, 15, v4
	v_bfe_u32 v4, v85, 4, 4
	s_nop 0
	v_cndmask_b32_e32 v16, v7, v46, vcc
	v_cmp_eq_u32_e32 vcc, 0, v4
	v_lshl_add_u32 v5, v16, 7, v5
	s_nop 0
	v_cndmask_b32_e32 v7, 0, v72, vcc
	v_cmp_eq_u32_e64 s[100:101], 1, v4
	v_cmp_eq_u32_e64 s[98:99], 2, v4
	v_cmp_eq_u32_e32 vcc, 3, v4
	v_cndmask_b32_e64 v7, v7, v71, s[100:101]
	v_cmp_eq_u32_e64 s[100:101], 4, v4
	v_cndmask_b32_e64 v7, v7, v70, s[98:99]
	v_cmp_eq_u32_e64 s[98:99], 5, v4
	v_cndmask_b32_e32 v7, v7, v69, vcc
	v_cmp_eq_u32_e32 vcc, 6, v4
	v_cndmask_b32_e64 v7, v7, v68, s[100:101]
	v_cmp_eq_u32_e64 s[100:101], 7, v4
	v_cndmask_b32_e64 v7, v7, v67, s[98:99]
	v_cmp_eq_u32_e64 s[98:99], 8, v4
	v_cndmask_b32_e32 v7, v7, v61, vcc
	v_cmp_eq_u32_e32 vcc, 9, v4
	v_cndmask_b32_e64 v7, v7, v60, s[100:101]
	v_cmp_eq_u32_e64 s[100:101], 10, v4
	v_cndmask_b32_e64 v7, v7, v53, s[98:99]
	v_cmp_eq_u32_e64 s[98:99], 11, v4
	v_cndmask_b32_e32 v7, v7, v52, vcc
	v_cmp_eq_u32_e32 vcc, 12, v4
	v_cndmask_b32_e64 v7, v7, v51, s[100:101]
	v_cmp_eq_u32_e64 s[100:101], 13, v4
	v_cndmask_b32_e64 v7, v7, v50, s[98:99]
	v_cmp_eq_u32_e64 s[98:99], 14, v4
	v_cndmask_b32_e32 v7, v7, v49, vcc
	v_cmp_eq_u32_e32 vcc, 15, v4
	v_cndmask_b32_e64 v7, v7, v48, s[100:101]
	v_cndmask_b32_e64 v7, v7, v47, s[98:99]
	v_cndmask_b32_e32 v4, v7, v46, vcc
	v_and_b32_e32 v7, 15, v85
	v_cmp_eq_u32_e32 vcc, 0, v7
	v_cmp_eq_u32_e64 s[100:101], 1, v7
	v_cmp_eq_u32_e64 s[98:99], 2, v7
	v_cndmask_b32_e32 v8, 0, v45, vcc
; __device__ __forceinline__ void phase_route(CArgs& A, int l, unsigned char* lds, int tid) {
;     ...
;         for (int k = 0; k < 16; ++k) { const unsigned ci = L3[k] & 0xFFu, i = ci >> 4, j = ci & 15u; unsigned e1 = 0u, e2 = 0u;
; #pragma unroll
;             for (int ii = 0; ii < 16; ++ii) { e1 = (i == (unsigned)ii) ? (L1[ii] & 0x7Fu) : e1; e2 = (j == (unsigned)ii) ? (L2[ii] & 0x7Fu) : e2; }
;             ex[k] = (int)(e1 * 128u + e2); e[k] *= inv; }
	v_cmp_eq_u32_e32 vcc, 3, v7
	v_cndmask_b32_e64 v8, v8, v44, s[100:101]
	v_cmp_eq_u32_e64 s[100:101], 4, v7
	v_cndmask_b32_e64 v8, v8, v43, s[98:99]
	v_cmp_eq_u32_e64 s[98:99], 5, v7
	v_cndmask_b32_e32 v8, v8, v42, vcc
	v_cmp_eq_u32_e32 vcc, 6, v7
	v_cndmask_b32_e64 v8, v8, v41, s[100:101]
	v_cmp_eq_u32_e64 s[100:101], 7, v7
	v_cndmask_b32_e64 v8, v8, v40, s[98:99]
	v_cmp_eq_u32_e64 s[98:99], 8, v7
	v_cndmask_b32_e32 v8, v8, v39, vcc
	v_cmp_eq_u32_e32 vcc, 9, v7
	v_cndmask_b32_e64 v8, v8, v38, s[100:101]
	v_cmp_eq_u32_e64 s[100:101], 10, v7
	v_cndmask_b32_e64 v8, v8, v37, s[98:99]
	v_cmp_eq_u32_e64 s[98:99], 11, v7
	v_cndmask_b32_e32 v8, v8, v36, vcc
	v_cmp_eq_u32_e32 vcc, 12, v7
	v_cndmask_b32_e64 v8, v8, v35, s[100:101]
	v_cmp_eq_u32_e64 s[100:101], 13, v7
	v_cndmask_b32_e64 v8, v8, v34, s[98:99]
	v_cmp_eq_u32_e64 s[98:99], 14, v7
	v_cndmask_b32_e32 v8, v8, v33, vcc
	v_cmp_eq_u32_e32 vcc, 15, v7
	v_cndmask_b32_e64 v8, v8, v32, s[100:101]
	v_cndmask_b32_e64 v8, v8, v11, s[98:99]
	v_cndmask_b32_e32 v7, v8, v6, vcc
	v_lshl_add_u32 v4, v4, 7, v7
	v_bfe_u32 v7, v3, 4, 4
	v_cmp_eq_u32_e32 vcc, 0, v7
	v_and_b32_e32 v3, 15, v3
	s_nop 0
	v_cndmask_b32_e32 v8, 0, v72, vcc
	v_cmp_eq_u32_e32 vcc, 1, v7
	v_cmp_eq_u32_e64 s[100:101], 2, v7
	v_cmp_eq_u32_e64 s[98:99], 3, v7
	v_cndmask_b32_e32 v8, v8, v71, vcc
	v_cmp_eq_u32_e32 vcc, 4, v7
	v_cndmask_b32_e64 v8, v8, v70, s[100:101]
	v_cmp_eq_u32_e64 s[100:101], 5, v7
	v_cndmask_b32_e64 v8, v8, v69, s[98:99]
	v_cmp_eq_u32_e64 s[98:99], 6, v7
	v_cndmask_b32_e32 v8, v8, v68, vcc
	v_cmp_eq_u32_e32 vcc, 7, v7
	v_cndmask_b32_e64 v8, v8, v67, s[100:101]
	v_cmp_eq_u32_e64 s[100:101], 8, v7
	v_cndmask_b32_e64 v8, v8, v61, s[98:99]
	v_cmp_eq_u32_e64 s[98:99], 9, v7
	v_cndmask_b32_e32 v8, v8, v60, vcc
	v_cmp_eq_u32_e32 vcc, 10, v7
	v_cndmask_b32_e64 v8, v8, v53, s[100:101]
	v_cmp_eq_u32_e64 s[100:101], 11, v7
	v_cndmask_b32_e64 v8, v8, v52, s[98:99]
	v_cmp_eq_u32_e64 s[98:99], 12, v7
	v_cndmask_b32_e32 v8, v8, v51, vcc
	v_cmp_eq_u32_e32 vcc, 13, v7
	v_cndmask_b32_e64 v8, v8, v50, s[100:101]
	v_cmp_eq_u32_e64 s[100:101], 14, v7
	v_cndmask_b32_e64 v8, v8, v49, s[98:99]
	v_cmp_eq_u32_e64 s[98:99], 15, v7
	v_cndmask_b32_e32 v8, v8, v48, vcc
	v_cmp_eq_u32_e32 vcc, 0, v3
	v_cndmask_b32_e64 v8, v8, v47, s[100:101]
	v_cmp_eq_u32_e64 s[100:101], 1, v3
	v_cndmask_b32_e64 v7, v8, v46, s[98:99]
	v_cmp_eq_u32_e64 s[98:99], 2, v3
	v_cndmask_b32_e32 v8, 0, v45, vcc
	v_cmp_eq_u32_e32 vcc, 3, v3
	v_cndmask_b32_e64 v8, v8, v44, s[100:101]
	v_cmp_eq_u32_e64 s[100:101], 4, v3
	v_cndmask_b32_e64 v8, v8, v43, s[98:99]
	v_cmp_eq_u32_e64 s[98:99], 5, v3
	v_cndmask_b32_e32 v8, v8, v42, vcc
	v_cmp_eq_u32_e32 vcc, 6, v3
	v_cndmask_b32_e64 v8, v8, v41, s[100:101]
	v_cmp_eq_u32_e64 s[100:101], 7, v3
	v_cndmask_b32_e64 v8, v8, v40, s[98:99]
	v_cmp_eq_u32_e64 s[98:99], 8, v3
	v_cndmask_b32_e32 v8, v8, v39, vcc
	v_cmp_eq_u32_e32 vcc, 9, v3
	v_cndmask_b32_e64 v8, v8, v38, s[100:101]
	v_cmp_eq_u32_e64 s[100:101], 10, v3
	v_cndmask_b32_e64 v8, v8, v37, s[98:99]
	v_cmp_eq_u32_e64 s[98:99], 11, v3
	v_cndmask_b32_e32 v8, v8, v36, vcc
	v_cmp_eq_u32_e32 vcc, 12, v3
	v_cndmask_b32_e64 v8, v8, v35, s[100:101]
	v_cmp_eq_u32_e64 s[100:101], 13, v3
	v_cndmask_b32_e64 v8, v8, v34, s[98:99]
	v_cmp_eq_u32_e64 s[98:99], 14, v3
	v_cndmask_b32_e32 v8, v8, v33, vcc
	v_cmp_eq_u32_e32 vcc, 15, v3
	v_cndmask_b32_e64 v8, v8, v32, s[100:101]
	v_cndmask_b32_e64 v8, v8, v11, s[98:99]
	v_cndmask_b32_e32 v3, v8, v6, vcc
	v_lshl_add_u32 v3, v7, 7, v3
	v_bfe_u32 v7, v2, 4, 4
	v_cmp_eq_u32_e32 vcc, 0, v7
	v_and_b32_e32 v2, 15, v2
	s_nop 0
	v_cndmask_b32_e32 v8, 0, v72, vcc
	v_cmp_eq_u32_e32 vcc, 1, v7
	v_cmp_eq_u32_e64 s[100:101], 2, v7
	v_cmp_eq_u32_e64 s[98:99], 3, v7
	v_cndmask_b32_e32 v8, v8, v71, vcc
	v_cmp_eq_u32_e32 vcc, 4, v7
	v_cndmask_b32_e64 v8, v8, v70, s[100:101]
	v_cmp_eq_u32_e64 s[100:101], 5, v7
	v_cndmask_b32_e64 v8, v8, v69, s[98:99]
	v_cmp_eq_u32_e64 s[98:99], 6, v7
	v_cndmask_b32_e32 v8, v8, v68, vcc
	v_cmp_eq_u32_e32 vcc, 7, v7
	v_cndmask_b32_e64 v8, v8, v67, s[100:101]
	v_cmp_eq_u32_e64 s[100:101], 8, v7
	v_cndmask_b32_e64 v8, v8, v61, s[98:99]
	v_cmp_eq_u32_e64 s[98:99], 9, v7
	v_cndmask_b32_e32 v8, v8, v60, vcc
	v_cmp_eq_u32_e32 vcc, 10, v7
	v_cndmask_b32_e64 v8, v8, v53, s[100:101]
	v_cmp_eq_u32_e64 s[100:101], 11, v7
	v_cndmask_b32_e64 v8, v8, v52, s[98:99]
	v_cmp_eq_u32_e64 s[98:99], 12, v7
	v_cndmask_b32_e32 v8, v8, v51, vcc
	v_cmp_eq_u32_e32 vcc, 13, v7
	v_cndmask_b32_e64 v8, v8, v50, s[100:101]
	v_cmp_eq_u32_e64 s[100:101], 14, v7
	v_cndmask_b32_e64 v8, v8, v49, s[98:99]
	v_cmp_eq_u32_e64 s[98:99], 15, v7
	v_cndmask_b32_e32 v8, v8, v48, vcc
	v_cmp_eq_u32_e32 vcc, 0, v2
	v_cndmask_b32_e64 v8, v8, v47, s[100:101]
	v_cmp_eq_u32_e64 s[100:101], 1, v2
	v_cndmask_b32_e64 v7, v8, v46, s[98:99]
	v_cmp_eq_u32_e64 s[98:99], 2, v2
	v_cndmask_b32_e32 v8, 0, v45, vcc
	v_cmp_eq_u32_e32 vcc, 3, v2
	v_cndmask_b32_e64 v8, v8, v44, s[100:101]
	v_cmp_eq_u32_e64 s[100:101], 4, v2
	v_cndmask_b32_e64 v8, v8, v43, s[98:99]
	v_cmp_eq_u32_e64 s[98:99], 5, v2
	v_cndmask_b32_e32 v8, v8, v42, vcc
	v_cmp_eq_u32_e32 vcc, 6, v2
	v_cndmask_b32_e64 v8, v8, v41, s[100:101]
	v_cmp_eq_u32_e64 s[100:101], 7, v2
	v_cndmask_b32_e64 v8, v8, v40, s[98:99]
	v_cmp_eq_u32_e64 s[98:99], 8, v2
	v_cndmask_b32_e32 v8, v8, v39, vcc
	v_cmp_eq_u32_e32 vcc, 9, v2
	v_cndmask_b32_e64 v8, v8, v38, s[100:101]
	v_cmp_eq_u32_e64 s[100:101], 10, v2
	v_cndmask_b32_e64 v8, v8, v37, s[98:99]
	v_cmp_eq_u32_e64 s[98:99], 11, v2
	v_cndmask_b32_e32 v8, v8, v36, vcc
	v_cmp_eq_u32_e32 vcc, 12, v2
	v_cndmask_b32_e64 v8, v8, v35, s[100:101]
	v_cmp_eq_u32_e64 s[100:101], 13, v2
	v_cndmask_b32_e64 v8, v8, v34, s[98:99]
; __device__ __forceinline__ void phase_route(CArgs& A, int l, unsigned char* lds, int tid) {
;     ...
;         for (int k = 0; k < 16; ++k) { const unsigned ci = L3[k] & 0xFFu, i = ci >> 4, j = ci & 15u; unsigned e1 = 0u, e2 = 0u;
; #pragma unroll
;             for (int ii = 0; ii < 16; ++ii) { e1 = (i == (unsigned)ii) ? (L1[ii] & 0x7Fu) : e1; e2 = (j == (unsigned)ii) ? (L2[ii] & 0x7Fu) : e2; }
;             ex[k] = (int)(e1 * 128u + e2); e[k] *= inv; }
	v_cmp_eq_u32_e64 s[98:99], 14, v2
	v_cndmask_b32_e32 v8, v8, v33, vcc
	v_cmp_eq_u32_e32 vcc, 15, v2
	v_cndmask_b32_e64 v8, v8, v32, s[100:101]
	v_cndmask_b32_e64 v8, v8, v11, s[98:99]
	v_cndmask_b32_e32 v2, v8, v6, vcc
	v_lshl_add_u32 v2, v7, 7, v2
	v_bfe_u32 v7, v81, 4, 4
	v_cmp_eq_u32_e32 vcc, 0, v7
	v_cmp_eq_u32_e64 s[100:101], 1, v7
	v_cmp_eq_u32_e64 s[98:99], 2, v7
	v_cndmask_b32_e32 v8, 0, v72, vcc
	v_cmp_eq_u32_e32 vcc, 3, v7
	v_cndmask_b32_e64 v8, v8, v71, s[100:101]
	v_cmp_eq_u32_e64 s[100:101], 4, v7
	v_cndmask_b32_e64 v8, v8, v70, s[98:99]
	v_cmp_eq_u32_e64 s[98:99], 5, v7
	v_cndmask_b32_e32 v8, v8, v69, vcc
	v_cmp_eq_u32_e32 vcc, 6, v7
	v_cndmask_b32_e64 v8, v8, v68, s[100:101]
	v_cmp_eq_u32_e64 s[100:101], 7, v7
	v_cndmask_b32_e64 v8, v8, v67, s[98:99]
	v_cmp_eq_u32_e64 s[98:99], 8, v7
	v_cndmask_b32_e32 v8, v8, v61, vcc
	v_cmp_eq_u32_e32 vcc, 9, v7
	v_cndmask_b32_e64 v8, v8, v60, s[100:101]
	v_cmp_eq_u32_e64 s[100:101], 10, v7
	v_cndmask_b32_e64 v8, v8, v53, s[98:99]
	v_cmp_eq_u32_e64 s[98:99], 11, v7
	v_cndmask_b32_e32 v8, v8, v52, vcc
	v_cmp_eq_u32_e32 vcc, 12, v7
	v_cndmask_b32_e64 v8, v8, v51, s[100:101]
	v_cmp_eq_u32_e64 s[100:101], 13, v7
	v_cndmask_b32_e64 v8, v8, v50, s[98:99]
	v_cmp_eq_u32_e64 s[98:99], 14, v7
	v_cndmask_b32_e32 v8, v8, v49, vcc
	v_cmp_eq_u32_e32 vcc, 15, v7
	v_cndmask_b32_e64 v8, v8, v48, s[100:101]
	v_cndmask_b32_e64 v8, v8, v47, s[98:99]
	v_cndmask_b32_e32 v7, v8, v46, vcc
	v_and_b32_e32 v8, 15, v81
	v_cmp_eq_u32_e32 vcc, 0, v8
	v_cmp_eq_u32_e64 s[100:101], 1, v8
	v_cmp_eq_u32_e64 s[98:99], 2, v8
	v_cndmask_b32_e32 v9, 0, v45, vcc
	v_cmp_eq_u32_e32 vcc, 3, v8
	v_cndmask_b32_e64 v9, v9, v44, s[100:101]
	v_cmp_eq_u32_e64 s[100:101], 4, v8
	v_cndmask_b32_e64 v9, v9, v43, s[98:99]
	v_cmp_eq_u32_e64 s[98:99], 5, v8
	v_cndmask_b32_e32 v9, v9, v42, vcc
	v_cmp_eq_u32_e32 vcc, 6, v8
	v_cndmask_b32_e64 v9, v9, v41, s[100:101]
	v_cmp_eq_u32_e64 s[100:101], 7, v8
	v_cndmask_b32_e64 v9, v9, v40, s[98:99]
	v_cmp_eq_u32_e64 s[98:99], 8, v8
	v_cndmask_b32_e32 v9, v9, v39, vcc
	v_cmp_eq_u32_e32 vcc, 9, v8
	v_cndmask_b32_e64 v9, v9, v38, s[100:101]
	v_cmp_eq_u32_e64 s[100:101], 10, v8
	v_cndmask_b32_e64 v9, v9, v37, s[98:99]
	v_cmp_eq_u32_e64 s[98:99], 11, v8
	v_cndmask_b32_e32 v9, v9, v36, vcc
	v_cmp_eq_u32_e32 vcc, 12, v8
	v_cndmask_b32_e64 v9, v9, v35, s[100:101]
	v_cmp_eq_u32_e64 s[100:101], 13, v8
	v_cndmask_b32_e64 v9, v9, v34, s[98:99]
	v_cmp_eq_u32_e64 s[98:99], 14, v8
	v_cndmask_b32_e32 v9, v9, v33, vcc
	v_cmp_eq_u32_e32 vcc, 15, v8
	v_cndmask_b32_e64 v9, v9, v32, s[100:101]
	v_cndmask_b32_e64 v9, v9, v11, s[98:99]
	v_cndmask_b32_e32 v8, v9, v6, vcc
	v_lshl_add_u32 v9, v7, 7, v8
	v_bfe_u32 v7, v79, 4, 4
	v_cmp_eq_u32_e32 vcc, 0, v7
	v_cmp_eq_u32_e64 s[100:101], 1, v7
	v_cmp_eq_u32_e64 s[98:99], 2, v7
	v_cndmask_b32_e32 v8, 0, v72, vcc
	v_cmp_eq_u32_e32 vcc, 3, v7
	v_cndmask_b32_e64 v8, v8, v71, s[100:101]
	v_cmp_eq_u32_e64 s[100:101], 4, v7
	v_cndmask_b32_e64 v8, v8, v70, s[98:99]
	v_cmp_eq_u32_e64 s[98:99], 5, v7
	v_cndmask_b32_e32 v8, v8, v69, vcc
	v_cmp_eq_u32_e32 vcc, 6, v7
	v_cndmask_b32_e64 v8, v8, v68, s[100:101]
	v_cmp_eq_u32_e64 s[100:101], 7, v7
	v_cndmask_b32_e64 v8, v8, v67, s[98:99]
	v_cmp_eq_u32_e64 s[98:99], 8, v7
	v_cndmask_b32_e32 v8, v8, v61, vcc
	v_cmp_eq_u32_e32 vcc, 9, v7
	v_cndmask_b32_e64 v8, v8, v60, s[100:101]
	v_cmp_eq_u32_e64 s[100:101], 10, v7
	v_cndmask_b32_e64 v8, v8, v53, s[98:99]
	v_cmp_eq_u32_e64 s[98:99], 11, v7
	v_cndmask_b32_e32 v8, v8, v52, vcc
	v_cmp_eq_u32_e32 vcc, 12, v7
	v_cndmask_b32_e64 v8, v8, v51, s[100:101]
	v_cmp_eq_u32_e64 s[100:101], 13, v7
	v_cndmask_b32_e64 v8, v8, v50, s[98:99]
	v_cmp_eq_u32_e64 s[98:99], 14, v7
	v_cndmask_b32_e32 v8, v8, v49, vcc
	v_cmp_eq_u32_e32 vcc, 15, v7
	v_cndmask_b32_e64 v8, v8, v48, s[100:101]
	v_cndmask_b32_e64 v8, v8, v47, s[98:99]
	v_cndmask_b32_e32 v7, v8, v46, vcc
	v_and_b32_e32 v8, 15, v79
	v_cmp_eq_u32_e32 vcc, 0, v8
	v_cmp_eq_u32_e64 s[100:101], 1, v8
	v_cmp_eq_u32_e64 s[98:99], 2, v8
	v_cndmask_b32_e32 v17, 0, v45, vcc
	v_cmp_eq_u32_e32 vcc, 3, v8
	v_cndmask_b32_e64 v17, v17, v44, s[100:101]
	v_cmp_eq_u32_e64 s[100:101], 4, v8
	v_cndmask_b32_e64 v17, v17, v43, s[98:99]
	v_cmp_eq_u32_e64 s[98:99], 5, v8
	v_cndmask_b32_e32 v17, v17, v42, vcc
	v_cmp_eq_u32_e32 vcc, 6, v8
	v_cndmask_b32_e64 v17, v17, v41, s[100:101]
	v_cmp_eq_u32_e64 s[100:101], 7, v8
	v_cndmask_b32_e64 v17, v17, v40, s[98:99]
	v_cmp_eq_u32_e64 s[98:99], 8, v8
	v_cndmask_b32_e32 v17, v17, v39, vcc
	v_cmp_eq_u32_e32 vcc, 9, v8
	v_cndmask_b32_e64 v17, v17, v38, s[100:101]
	v_cmp_eq_u32_e64 s[100:101], 10, v8
	v_cndmask_b32_e64 v17, v17, v37, s[98:99]
	v_cmp_eq_u32_e64 s[98:99], 11, v8
	v_cndmask_b32_e32 v17, v17, v36, vcc
	v_cmp_eq_u32_e32 vcc, 12, v8
	v_cndmask_b32_e64 v17, v17, v35, s[100:101]
	v_cmp_eq_u32_e64 s[100:101], 13, v8
	v_cndmask_b32_e64 v17, v17, v34, s[98:99]
	v_cmp_eq_u32_e64 s[98:99], 14, v8
	v_cndmask_b32_e32 v17, v17, v33, vcc
	v_cmp_eq_u32_e32 vcc, 15, v8
	v_cndmask_b32_e64 v17, v17, v32, s[100:101]
	v_cndmask_b32_e64 v17, v17, v11, s[98:99]
	v_cndmask_b32_e32 v8, v17, v6, vcc
	v_lshl_add_u32 v8, v7, 7, v8
	v_bfe_u32 v7, v77, 4, 4
	v_cmp_eq_u32_e32 vcc, 0, v7
	v_cmp_eq_u32_e64 s[100:101], 1, v7
; __device__ __forceinline__ void phase_route(CArgs& A, int l, unsigned char* lds, int tid) {
;     ...
;         for (int k = 0; k < 16; ++k) { const unsigned ci = L3[k] & 0xFFu, i = ci >> 4, j = ci & 15u; unsigned e1 = 0u, e2 = 0u;
; #pragma unroll
;             for (int ii = 0; ii < 16; ++ii) { e1 = (i == (unsigned)ii) ? (L1[ii] & 0x7Fu) : e1; e2 = (j == (unsigned)ii) ? (L2[ii] & 0x7Fu) : e2; }
;             ex[k] = (int)(e1 * 128u + e2); e[k] *= inv; }
;         int* ip = IDX + (size_t)t * 128 + hd * 16; float* gp = GATE + (size_t)t * 128 + hd * 16;
;         if (hf == 0) {
;             *(int4*)ip = make_int4(ex[0], ex[1], ex[2], ex[3]); *(int4*)(ip + 4) = make_int4(ex[4], ex[5], ex[6], ex[7]);
;             *(f32x4*)gp = (f32x4){e[0], e[1], e[2], e[3]}; *(f32x4*)(gp + 4) = (f32x4){e[4], e[5], e[6], e[7]};
;         } else {
;             *(int4*)(ip + 8) = make_int4(ex[8], ex[9], ex[10], ex[11]); *(int4*)(ip + 12) = make_int4(ex[12], ex[13], ex[14], ex[15]);
;             *(f32x4*)(gp + 8) = (f32x4){e[8], e[9], e[10], e[11]}; *(f32x4*)(gp + 12) = (f32x4){e[12], e[13], e[14], e[15]};
	v_cmp_eq_u32_e64 s[98:99], 2, v7
	v_cndmask_b32_e32 v17, 0, v72, vcc
	v_cmp_eq_u32_e32 vcc, 3, v7
	v_cndmask_b32_e64 v17, v17, v71, s[100:101]
	v_cmp_eq_u32_e64 s[100:101], 4, v7
	v_cndmask_b32_e64 v17, v17, v70, s[98:99]
	v_cmp_eq_u32_e64 s[98:99], 5, v7
	v_cndmask_b32_e32 v17, v17, v69, vcc
	v_cmp_eq_u32_e32 vcc, 6, v7
	v_cndmask_b32_e64 v17, v17, v68, s[100:101]
	v_cmp_eq_u32_e64 s[100:101], 7, v7
	v_cndmask_b32_e64 v17, v17, v67, s[98:99]
	v_cmp_eq_u32_e64 s[98:99], 8, v7
	v_cndmask_b32_e32 v17, v17, v61, vcc
	v_cmp_eq_u32_e32 vcc, 9, v7
	v_cndmask_b32_e64 v17, v17, v60, s[100:101]
	v_cmp_eq_u32_e64 s[100:101], 10, v7
	v_cndmask_b32_e64 v17, v17, v53, s[98:99]
	v_cmp_eq_u32_e64 s[98:99], 11, v7
	v_cndmask_b32_e32 v17, v17, v52, vcc
	v_cmp_eq_u32_e32 vcc, 12, v7
	v_cndmask_b32_e64 v17, v17, v51, s[100:101]
	v_cmp_eq_u32_e64 s[100:101], 13, v7
	v_cndmask_b32_e64 v17, v17, v50, s[98:99]
	v_cmp_eq_u32_e64 s[98:99], 14, v7
	v_cndmask_b32_e32 v17, v17, v49, vcc
	v_cmp_eq_u32_e32 vcc, 15, v7
	v_cndmask_b32_e64 v17, v17, v48, s[100:101]
	v_cndmask_b32_e64 v17, v17, v47, s[98:99]
	v_cndmask_b32_e32 v7, v17, v46, vcc
	v_and_b32_e32 v17, 15, v77
	v_cmp_eq_u32_e32 vcc, 0, v17
	v_cmp_eq_u32_e64 s[100:101], 1, v17
	v_cmp_eq_u32_e64 s[98:99], 2, v17
	v_cndmask_b32_e32 v18, 0, v45, vcc
	v_cmp_eq_u32_e32 vcc, 3, v17
	v_cndmask_b32_e64 v18, v18, v44, s[100:101]
	v_cmp_eq_u32_e64 s[100:101], 4, v17
	v_cndmask_b32_e64 v18, v18, v43, s[98:99]
	v_cmp_eq_u32_e64 s[98:99], 5, v17
	v_cndmask_b32_e32 v18, v18, v42, vcc
	v_cmp_eq_u32_e32 vcc, 6, v17
	v_cndmask_b32_e64 v18, v18, v41, s[100:101]
	v_cmp_eq_u32_e64 s[100:101], 7, v17
	v_cndmask_b32_e64 v18, v18, v40, s[98:99]
	v_cmp_eq_u32_e64 s[98:99], 8, v17
	v_cndmask_b32_e32 v18, v18, v39, vcc
	v_cmp_eq_u32_e32 vcc, 9, v17
	v_cndmask_b32_e64 v18, v18, v38, s[100:101]
	v_cmp_eq_u32_e64 s[100:101], 10, v17
	v_cndmask_b32_e64 v18, v18, v37, s[98:99]
	v_cmp_eq_u32_e64 s[98:99], 11, v17
	v_cndmask_b32_e32 v18, v18, v36, vcc
	v_cmp_eq_u32_e32 vcc, 12, v17
	v_cndmask_b32_e64 v18, v18, v35, s[100:101]
	v_cmp_eq_u32_e64 s[100:101], 13, v17
	v_cndmask_b32_e64 v18, v18, v34, s[98:99]
	v_cmp_eq_u32_e64 s[98:99], 14, v17
	v_cndmask_b32_e32 v18, v18, v33, vcc
	v_cmp_eq_u32_e32 vcc, 15, v17
	v_cndmask_b32_e64 v18, v18, v32, s[100:101]
	v_cndmask_b32_e64 v18, v18, v11, s[98:99]
	v_cndmask_b32_e32 v17, v18, v6, vcc
	v_lshl_add_u32 v7, v7, 7, v17
	v_bfe_u32 v17, v75, 4, 4
	v_cmp_eq_u32_e32 vcc, 0, v17
	v_cmp_eq_u32_e64 s[100:101], 1, v17
	v_cmp_eq_u32_e64 s[98:99], 2, v17
	v_cndmask_b32_e32 v18, 0, v72, vcc
	v_cmp_eq_u32_e32 vcc, 3, v17
	v_cndmask_b32_e64 v18, v18, v71, s[100:101]
	v_cmp_eq_u32_e64 s[100:101], 4, v17
	v_cndmask_b32_e64 v18, v18, v70, s[98:99]
	v_cmp_eq_u32_e64 s[98:99], 5, v17
	v_cndmask_b32_e32 v18, v18, v69, vcc
	v_cmp_eq_u32_e32 vcc, 6, v17
	v_cndmask_b32_e64 v18, v18, v68, s[100:101]
	v_cmp_eq_u32_e64 s[100:101], 7, v17
	v_cndmask_b32_e64 v18, v18, v67, s[98:99]
	v_cmp_eq_u32_e64 s[98:99], 8, v17
	v_cndmask_b32_e32 v18, v18, v61, vcc
	v_cmp_eq_u32_e32 vcc, 9, v17
	v_cndmask_b32_e64 v18, v18, v60, s[100:101]
	v_cmp_eq_u32_e64 s[100:101], 10, v17
	v_cndmask_b32_e64 v18, v18, v53, s[98:99]
	v_cmp_eq_u32_e64 s[98:99], 11, v17
	v_cndmask_b32_e32 v18, v18, v52, vcc
	v_cmp_eq_u32_e32 vcc, 12, v17
	v_cndmask_b32_e64 v18, v18, v51, s[100:101]
	v_cmp_eq_u32_e64 s[100:101], 13, v17
	v_cndmask_b32_e64 v18, v18, v50, s[98:99]
	v_cmp_eq_u32_e64 s[98:99], 14, v17
	v_cndmask_b32_e32 v18, v18, v49, vcc
	v_cmp_eq_u32_e32 vcc, 15, v17
	v_cndmask_b32_e64 v18, v18, v48, s[100:101]
	v_cndmask_b32_e64 v18, v18, v47, s[98:99]
	v_cndmask_b32_e32 v17, v18, v46, vcc
	v_and_b32_e32 v18, 15, v75
	v_cmp_eq_u32_e32 vcc, 0, v18
	v_cmp_eq_u32_e64 s[100:101], 1, v18
	v_cmp_eq_u32_e64 s[98:99], 2, v18
	v_cndmask_b32_e32 v19, 0, v45, vcc
	v_cmp_eq_u32_e32 vcc, 3, v18
	v_cndmask_b32_e64 v19, v19, v44, s[100:101]
	v_cmp_eq_u32_e64 s[100:101], 4, v18
	v_cndmask_b32_e64 v19, v19, v43, s[98:99]
	v_cmp_eq_u32_e64 s[98:99], 5, v18
	v_cndmask_b32_e32 v19, v19, v42, vcc
	v_cmp_eq_u32_e32 vcc, 6, v18
	v_cndmask_b32_e64 v19, v19, v41, s[100:101]
	v_cmp_eq_u32_e64 s[100:101], 7, v18
	v_cndmask_b32_e64 v19, v19, v40, s[98:99]
	v_cmp_eq_u32_e64 s[98:99], 8, v18
	v_cndmask_b32_e32 v19, v19, v39, vcc
	v_cmp_eq_u32_e32 vcc, 9, v18
	v_cndmask_b32_e64 v19, v19, v38, s[100:101]
	v_cmp_eq_u32_e64 s[100:101], 10, v18
	v_cndmask_b32_e64 v19, v19, v37, s[98:99]
	v_cmp_eq_u32_e64 s[98:99], 11, v18
	v_cndmask_b32_e32 v19, v19, v36, vcc
	v_cmp_eq_u32_e32 vcc, 12, v18
	v_cndmask_b32_e64 v19, v19, v35, s[100:101]
	v_cmp_eq_u32_e64 s[100:101], 13, v18
	v_cndmask_b32_e64 v19, v19, v34, s[98:99]
	v_cmp_eq_u32_e64 s[98:99], 14, v18
	v_cndmask_b32_e32 v19, v19, v33, vcc
	v_cmp_eq_u32_e32 vcc, 15, v18
	v_cndmask_b32_e64 v19, v19, v32, s[100:101]
	v_cndmask_b32_e64 v11, v19, v11, s[98:99]
	v_cndmask_b32_e32 v6, v11, v6, vcc
	v_lshl_add_u32 v6, v17, 7, v6
	global_store_dwordx4 v[14:15], v[6:9], off offset:32
	global_store_dwordx4 v[14:15], v[2:5], off offset:48
	s_nop 1
	v_pk_mul_f32 v[4:5], v[26:27], v[10:11] op_sel_hi:[1,0]
	v_pk_mul_f32 v[2:3], v[24:25], v[10:11] op_sel_hi:[1,0]
	global_store_dwordx4 v[12:13], v[2:5], off offset:32
